# HNAQP2S + swiglu epilogue: the four per-row rstd ds_bpermute broadcasts of each row half issued together (2 exposed LDS round trips per unit instead of 8)
# speedup vs baseline: 1.0017x; 1.0017x over previous
; __device__ __forceinline__ unsigned cvt_pk_bf16(float lo, float hi) { unsigned r; asm volatile("v_cvt_pk_bf16_f32 %0, %1, %2" : "=v"(r) : "v"(lo), "v"(hi)); return r; }
; __device__ __forceinline__ float silu_mul(float a, float b) { return a * b * __builtin_amdgcn_rcpf(1.0f + __builtin_amdgcn_exp2f(-a * LOG2E)); }
; __device__ __forceinline__ float row_rstd(const float* ss, int row) { return 1.0f / sqrtf(ss[row] * (1.0f / DM) + 1e-6f); }
;     __device__ __forceinline__ void operator()(const f32x4 (&acc)[2][2][4][2], const Unit& u, int wr, int wc, int fr, int fq) const {
;         const int row0 = u.pm * BM + wr * 64 + fr, col0 = u.pn * HALF + wc * 32 + 8 * fq;
;         const int s = (u.pm < ML / BM) ? (u.pm >> 5) : 4;
;         const float* bp = bias + (size_t)s * BIAS_N + u.pn * BM + wc * 32 + 8 * fq;
;         const f32x4 ba0 = *(const f32x4*)bp, ba1 = *(const f32x4*)(bp + 4), bb0 = *(const f32x4*)(bp + HALF), bb1 = *(const f32x4*)(bp + HALF + 4);
;         const int lane = fq * 16 + fr;
;         const float rsl0 = row_rstd(ss, u.pm * BM + wr * 64 + lane), rsl1 = row_rstd(ss, u.pm * BM + HALF + wr * 64 + lane);
; #pragma unroll
;         for (int ai = 0; ai < 2; ++ai)
; #pragma unroll
;             for (int m = 0; m < 4; ++m) { const int row = row0 + ai * HALF + m * 16; const float rs = __shfl(ai ? rsl1 : rsl0, m * 16 + fr); bf16_t* rowp = O + (size_t)row * DFF + col0;
;                 const f32x4 a0 = acc[ai][0][m][0] * rs + ba0, a1 = acc[ai][0][m][1] * rs + ba1, b0 = acc[ai][1][m][0] * rs + bb0, b1 = acc[ai][1][m][1] * rs + bb1;
;                 u32x4 w; w.x = cvt_pk_bf16(silu_mul(a0[0], b0[0]), silu_mul(a0[1], b0[1])); w.y = cvt_pk_bf16(silu_mul(a0[2], b0[2]), silu_mul(a0[3], b0[3]));
;                 w.z = cvt_pk_bf16(silu_mul(a1[0], b1[0]), silu_mul(a1[1], b1[1])); w.w = cvt_pk_bf16(silu_mul(a1[2], b1[2]), silu_mul(a1[3], b1[3]));
;                 *(u32x4*)rowp = w; }
.LBB0_193:
	s_lshl_b32 s2, s2, 8
	s_add_i32 s12, s2, s54
	s_lshl_b64 s[2:3], s[16:17], 2
	s_add_u32 s13, s68, s2
	s_addc_u32 s14, s69, s3
	s_lshl_b32 s2, s0, 8
	s_ashr_i32 s3, s2, 31
	s_lshl_b64 s[2:3], s[2:3], 2
	v_lshl_or_b32 v164, s0, 7, v173
	s_add_u32 s0, s13, s2
	s_addc_u32 s3, s14, s3
	v_or_b32_e32 v162, s12, v171
	s_add_u32 s2, s0, s60
	v_ashrrev_i32_e32 v163, 31, v162
	s_addc_u32 s3, s3, 0
	v_lshl_add_u64 v[162:163], v[162:163], 2, s[8:9]
	v_mov_b32_e32 v74, v234
	v_mov_b32_e32 v75, v235
	v_mov_b32_e32 v76, v236
	v_mov_b32_e32 v77, v237
	v_mov_b32_e32 v78, v238
	v_mov_b32_e32 v79, v239
	v_mov_b32_e32 v80, v240
	v_mov_b32_e32 v81, v241
	v_mov_b32_e32 v66, v242
	v_mov_b32_e32 v67, v243
	v_mov_b32_e32 v68, v244
	v_mov_b32_e32 v69, v245
	v_mov_b32_e32 v70, v246
	v_mov_b32_e32 v71, v247
	v_mov_b32_e32 v72, v248
	v_mov_b32_e32 v73, v249
	v_or_b32_e32 v181, s12, v169
	v_mov_b32_e32 v162, v250
	s_waitcnt vmcnt(0)
	v_fmamk_f32 v162, v162, 0x3a000000, v178
	v_cmp_gt_f32_e32 vcc, s61, v162
	v_mul_f32_e32 v163, 0x4f800000, v162
	s_nop 0
	v_cndmask_b32_e32 v162, v162, v163, vcc
	v_sqrt_f32_e32 v163, v162
	s_nop 0
	v_add_u32_e32 v165, -1, v163
	v_fma_f32 v166, -v165, v163, v162
	v_cmp_ge_f32_e64 s[2:3], 0, v166
	v_add_u32_e32 v166, 1, v163
	s_nop 0
	v_cndmask_b32_e64 v165, v163, v165, s[2:3]
	v_fma_f32 v163, -v166, v163, v162
	v_cmp_lt_f32_e64 s[2:3], 0, v163
	s_nop 1
	v_cndmask_b32_e64 v163, v165, v166, s[2:3]
	v_mul_f32_e32 v165, 0x37800000, v163
	v_cndmask_b32_e32 v163, v163, v165, vcc
	v_cmp_class_f32_e32 vcc, v162, v179
	s_nop 1
	v_cndmask_b32_e32 v166, v163, v162, vcc
	v_add_u32_e32 v162, s12, v172
	v_ashrrev_i32_e32 v163, 31, v162
	v_lshl_add_u64 v[162:163], v[162:163], 2, s[8:9]
	v_mov_b32_e32 v162, v251
	v_fmamk_f32 v162, v162, 0x3a000000, v178
	v_cmp_gt_f32_e32 vcc, s61, v162
	v_mul_f32_e32 v163, 0x4f800000, v162
	s_nop 0
	v_cndmask_b32_e32 v162, v162, v163, vcc
	v_sqrt_f32_e32 v163, v162
	s_nop 0
	v_add_u32_e32 v165, -1, v163
	v_fma_f32 v167, -v165, v163, v162
	v_cmp_ge_f32_e64 s[2:3], 0, v167
	v_add_u32_e32 v167, 1, v163
	s_nop 0
	v_cndmask_b32_e64 v165, v163, v165, s[2:3]
	v_fma_f32 v163, -v167, v163, v162
	v_cmp_lt_f32_e64 s[2:3], 0, v163
	s_nop 1
	v_cndmask_b32_e64 v163, v165, v167, s[2:3]
	v_mul_f32_e32 v165, 0x37800000, v163
	v_cndmask_b32_e32 v163, v163, v165, vcc
	v_cmp_class_f32_e32 vcc, v162, v179
	v_ashrrev_i32_e32 v165, 31, v164
	v_lshlrev_b64 v[164:165], 1, v[164:165]
	v_cndmask_b32_e32 v182, v163, v162, vcc
	v_div_scale_f32 v162, s[2:3], v166, v166, 1.0
	v_rcp_f32_e32 v163, v162
	s_nop 0
	v_fma_f32 v167, -v162, v163, 1.0
	v_fmac_f32_e32 v163, v167, v163
	v_div_scale_f32 v167, vcc, 1.0, v166, 1.0
	v_mul_f32_e32 v168, v167, v163
	v_fma_f32 v183, -v162, v168, v167
	v_fmac_f32_e32 v168, v183, v163
	v_fma_f32 v162, -v162, v168, v167
	v_div_fmas_f32 v162, v162, v163, v168
	v_div_fixup_f32 v183, v162, v166, 1.0
	s_mov_b32 s100, 0xbfb8aa3b
	ds_bpermute_b32 v242, v180, v183
	ds_bpermute_b32 v244, v180, v183 offset:64
	ds_bpermute_b32 v246, v180, v183 offset:128
	ds_bpermute_b32 v248, v180, v183 offset:192
	v_mov_b64_e32 v[162:163], s[96:97]
	v_mad_i64_i32 v[166:167], s[2:3], v181, s59, v[162:163]
	v_lshl_add_u64 v[166:167], v[166:167], 0, v[164:165]
	s_waitcnt lgkmcnt(0)
	v_pk_fma_f32 v[142:143], v[142:143], v[242:243], v[78:79] op_sel_hi:[1,0,1]
	v_pk_fma_f32 v[144:145], v[144:145], v[242:243], v[80:81] op_sel_hi:[1,0,1]
	v_pk_fma_f32 v[134:135], v[134:135], v[242:243], v[70:71] op_sel_hi:[1,0,1]
	v_pk_fma_f32 v[136:137], v[136:137], v[242:243], v[72:73] op_sel_hi:[1,0,1]
	v_pk_fma_f32 v[138:139], v[138:139], v[242:243], v[74:75] op_sel_hi:[1,0,1]
	v_pk_fma_f32 v[140:141], v[140:141], v[242:243], v[76:77] op_sel_hi:[1,0,1]
	v_pk_fma_f32 v[130:131], v[130:131], v[242:243], v[66:67] op_sel_hi:[1,0,1]
	v_pk_fma_f32 v[132:133], v[132:133], v[242:243], v[68:69] op_sel_hi:[1,0,1]
	v_pk_mul_f32 v[234:235], v[142:143], s[100:101] op_sel_hi:[1,0]
	v_pk_mul_f32 v[236:237], v[144:145], s[100:101] op_sel_hi:[1,0]
	v_exp_f32_e32 v234, v234
	v_exp_f32_e32 v235, v235
	v_exp_f32_e32 v236, v236
	v_exp_f32_e32 v237, v237
	v_pk_add_f32 v[234:235], v[234:235], 1.0 op_sel_hi:[1,0]
	v_pk_add_f32 v[236:237], v[236:237], 1.0 op_sel_hi:[1,0]
	v_rcp_f32_e32 v234, v234
	v_rcp_f32_e32 v235, v235
	v_rcp_f32_e32 v236, v236
	v_rcp_f32_e32 v237, v237
	v_pk_mul_f32 v[134:135], v[142:143], v[134:135]
	v_pk_mul_f32 v[136:137], v[144:145], v[136:137]
	v_pk_mul_f32 v[134:135], v[134:135], v[234:235]
	v_pk_mul_f32 v[136:137], v[136:137], v[236:237]
	v_cvt_pk_bf16_f32 v238, v134, v135
	v_cvt_pk_bf16_f32 v239, v136, v137
	v_pk_mul_f32 v[234:235], v[138:139], s[100:101] op_sel_hi:[1,0]
	v_pk_mul_f32 v[236:237], v[140:141], s[100:101] op_sel_hi:[1,0]
	v_exp_f32_e32 v234, v234
	v_exp_f32_e32 v235, v235
	v_exp_f32_e32 v236, v236
	v_exp_f32_e32 v237, v237
	v_pk_add_f32 v[234:235], v[234:235], 1.0 op_sel_hi:[1,0]
	v_pk_add_f32 v[236:237], v[236:237], 1.0 op_sel_hi:[1,0]
	v_rcp_f32_e32 v234, v234
	v_rcp_f32_e32 v235, v235
	v_rcp_f32_e32 v236, v236
	v_rcp_f32_e32 v237, v237
	v_pk_mul_f32 v[130:131], v[138:139], v[130:131]
	v_pk_mul_f32 v[132:133], v[140:141], v[132:133]
	v_pk_mul_f32 v[130:131], v[130:131], v[234:235]
	v_pk_mul_f32 v[132:133], v[132:133], v[236:237]
	v_cvt_pk_bf16_f32 v240, v130, v131
	v_cvt_pk_bf16_f32 v241, v132, v133
	global_store_dwordx4 v[166:167], v[238:241], off
	v_or_b32_e32 v131, 16, v181
	v_mad_i64_i32 v[132:133], s[2:3], v131, s59, v[162:163]
	v_lshl_add_u64 v[132:133], v[132:133], 0, v[164:165]
	v_pk_fma_f32 v[126:127], v[126:127], v[244:245], v[78:79] op_sel_hi:[1,0,1]
	v_pk_fma_f32 v[128:129], v[128:129], v[244:245], v[80:81] op_sel_hi:[1,0,1]
; __device__ __forceinline__ unsigned cvt_pk_bf16(float lo, float hi) { unsigned r; asm volatile("v_cvt_pk_bf16_f32 %0, %1, %2" : "=v"(r) : "v"(lo), "v"(hi)); return r; }
; __device__ __forceinline__ float row_rstd(const float* ss, int row) { return 1.0f / sqrtf(ss[row] * (1.0f / DM) + 1e-6f); }
; __device__ __forceinline__ float silu_mul(float a, float b) { return a * b * __builtin_amdgcn_rcpf(1.0f + __builtin_amdgcn_exp2f(-a * LOG2E)); }
;     __device__ __forceinline__ void operator()(const f32x4 (&acc)[2][2][4][2], const Unit& u, int wr, int wc, int fr, int fq) const {
;         const int row0 = u.pm * BM + wr * 64 + fr, col0 = u.pn * HALF + wc * 32 + 8 * fq;
;         const int s = (u.pm < ML / BM) ? (u.pm >> 5) : 4;
;         const float* bp = bias + (size_t)s * BIAS_N + u.pn * BM + wc * 32 + 8 * fq;
;         const f32x4 ba0 = *(const f32x4*)bp, ba1 = *(const f32x4*)(bp + 4), bb0 = *(const f32x4*)(bp + HALF), bb1 = *(const f32x4*)(bp + HALF + 4);
;         const int lane = fq * 16 + fr;
;         const float rsl0 = row_rstd(ss, u.pm * BM + wr * 64 + lane), rsl1 = row_rstd(ss, u.pm * BM + HALF + wr * 64 + lane);
; #pragma unroll
;         for (int ai = 0; ai < 2; ++ai)
; #pragma unroll
;             for (int m = 0; m < 4; ++m) { const int row = row0 + ai * HALF + m * 16; const float rs = __shfl(ai ? rsl1 : rsl0, m * 16 + fr); bf16_t* rowp = O + (size_t)row * DFF + col0;
;                 const f32x4 a0 = acc[ai][0][m][0] * rs + ba0, a1 = acc[ai][0][m][1] * rs + ba1, b0 = acc[ai][1][m][0] * rs + bb0, b1 = acc[ai][1][m][1] * rs + bb1;
;                 u32x4 w; w.x = cvt_pk_bf16(silu_mul(a0[0], b0[0]), silu_mul(a0[1], b0[1])); w.y = cvt_pk_bf16(silu_mul(a0[2], b0[2]), silu_mul(a0[3], b0[3]));
;                 w.z = cvt_pk_bf16(silu_mul(a1[0], b1[0]), silu_mul(a1[1], b1[1])); w.w = cvt_pk_bf16(silu_mul(a1[2], b1[2]), silu_mul(a1[3], b1[3]));
;                 *(u32x4*)rowp = w; }
	v_pk_fma_f32 v[118:119], v[118:119], v[244:245], v[70:71] op_sel_hi:[1,0,1]
	v_pk_fma_f32 v[120:121], v[120:121], v[244:245], v[72:73] op_sel_hi:[1,0,1]
	v_pk_fma_f32 v[122:123], v[122:123], v[244:245], v[74:75] op_sel_hi:[1,0,1]
	v_pk_fma_f32 v[124:125], v[124:125], v[244:245], v[76:77] op_sel_hi:[1,0,1]
	v_pk_fma_f32 v[114:115], v[114:115], v[244:245], v[66:67] op_sel_hi:[1,0,1]
	v_pk_fma_f32 v[116:117], v[116:117], v[244:245], v[68:69] op_sel_hi:[1,0,1]
	v_pk_mul_f32 v[234:235], v[126:127], s[100:101] op_sel_hi:[1,0]
	v_pk_mul_f32 v[236:237], v[128:129], s[100:101] op_sel_hi:[1,0]
	v_exp_f32_e32 v234, v234
	v_exp_f32_e32 v235, v235
	v_exp_f32_e32 v236, v236
	v_exp_f32_e32 v237, v237
	v_pk_add_f32 v[234:235], v[234:235], 1.0 op_sel_hi:[1,0]
	v_pk_add_f32 v[236:237], v[236:237], 1.0 op_sel_hi:[1,0]
	v_rcp_f32_e32 v234, v234
	v_rcp_f32_e32 v235, v235
	v_rcp_f32_e32 v236, v236
	v_rcp_f32_e32 v237, v237
	v_pk_mul_f32 v[118:119], v[126:127], v[118:119]
	v_pk_mul_f32 v[120:121], v[128:129], v[120:121]
	v_pk_mul_f32 v[118:119], v[118:119], v[234:235]
	v_pk_mul_f32 v[120:121], v[120:121], v[236:237]
	v_cvt_pk_bf16_f32 v238, v118, v119
	v_cvt_pk_bf16_f32 v239, v120, v121
	v_pk_mul_f32 v[234:235], v[122:123], s[100:101] op_sel_hi:[1,0]
	v_pk_mul_f32 v[236:237], v[124:125], s[100:101] op_sel_hi:[1,0]
	v_exp_f32_e32 v234, v234
	v_exp_f32_e32 v235, v235
	v_exp_f32_e32 v236, v236
	v_exp_f32_e32 v237, v237
	v_pk_add_f32 v[234:235], v[234:235], 1.0 op_sel_hi:[1,0]
	v_pk_add_f32 v[236:237], v[236:237], 1.0 op_sel_hi:[1,0]
	v_rcp_f32_e32 v234, v234
	v_rcp_f32_e32 v235, v235
	v_rcp_f32_e32 v236, v236
	v_rcp_f32_e32 v237, v237
	v_pk_mul_f32 v[114:115], v[122:123], v[114:115]
	v_pk_mul_f32 v[116:117], v[124:125], v[116:117]
	v_pk_mul_f32 v[114:115], v[114:115], v[234:235]
	v_pk_mul_f32 v[116:117], v[116:117], v[236:237]
	v_cvt_pk_bf16_f32 v240, v114, v115
	v_cvt_pk_bf16_f32 v241, v116, v117
	global_store_dwordx4 v[132:133], v[238:241], off
	v_or_b32_e32 v115, 32, v181
	v_mad_i64_i32 v[116:117], s[2:3], v115, s59, v[162:163]
	v_lshl_add_u64 v[116:117], v[116:117], 0, v[164:165]
	v_pk_fma_f32 v[110:111], v[110:111], v[246:247], v[78:79] op_sel_hi:[1,0,1]
	v_pk_fma_f32 v[112:113], v[112:113], v[246:247], v[80:81] op_sel_hi:[1,0,1]
	v_pk_fma_f32 v[102:103], v[102:103], v[246:247], v[70:71] op_sel_hi:[1,0,1]
	v_pk_fma_f32 v[104:105], v[104:105], v[246:247], v[72:73] op_sel_hi:[1,0,1]
	v_pk_fma_f32 v[106:107], v[106:107], v[246:247], v[74:75] op_sel_hi:[1,0,1]
	v_pk_fma_f32 v[108:109], v[108:109], v[246:247], v[76:77] op_sel_hi:[1,0,1]
	v_pk_fma_f32 v[98:99], v[98:99], v[246:247], v[66:67] op_sel_hi:[1,0,1]
	v_pk_fma_f32 v[100:101], v[100:101], v[246:247], v[68:69] op_sel_hi:[1,0,1]
	v_pk_mul_f32 v[234:235], v[110:111], s[100:101] op_sel_hi:[1,0]
	v_pk_mul_f32 v[236:237], v[112:113], s[100:101] op_sel_hi:[1,0]
	v_exp_f32_e32 v234, v234
	v_exp_f32_e32 v235, v235
	v_exp_f32_e32 v236, v236
	v_exp_f32_e32 v237, v237
	v_pk_add_f32 v[234:235], v[234:235], 1.0 op_sel_hi:[1,0]
	v_pk_add_f32 v[236:237], v[236:237], 1.0 op_sel_hi:[1,0]
	v_rcp_f32_e32 v234, v234
	v_rcp_f32_e32 v235, v235
	v_rcp_f32_e32 v236, v236
	v_rcp_f32_e32 v237, v237
	v_pk_mul_f32 v[102:103], v[110:111], v[102:103]
	v_pk_mul_f32 v[104:105], v[112:113], v[104:105]
	v_pk_mul_f32 v[102:103], v[102:103], v[234:235]
	v_pk_mul_f32 v[104:105], v[104:105], v[236:237]
	v_cvt_pk_bf16_f32 v238, v102, v103
	v_cvt_pk_bf16_f32 v239, v104, v105
	v_pk_mul_f32 v[234:235], v[106:107], s[100:101] op_sel_hi:[1,0]
	v_pk_mul_f32 v[236:237], v[108:109], s[100:101] op_sel_hi:[1,0]
	v_exp_f32_e32 v234, v234
	v_exp_f32_e32 v235, v235
	v_exp_f32_e32 v236, v236
	v_exp_f32_e32 v237, v237
	v_pk_add_f32 v[234:235], v[234:235], 1.0 op_sel_hi:[1,0]
	v_pk_add_f32 v[236:237], v[236:237], 1.0 op_sel_hi:[1,0]
	v_rcp_f32_e32 v234, v234
	v_rcp_f32_e32 v235, v235
	v_rcp_f32_e32 v236, v236
	v_rcp_f32_e32 v237, v237
	v_pk_mul_f32 v[98:99], v[106:107], v[98:99]
	v_pk_mul_f32 v[100:101], v[108:109], v[100:101]
	v_pk_mul_f32 v[98:99], v[98:99], v[234:235]
	v_pk_mul_f32 v[100:101], v[100:101], v[236:237]
	v_cvt_pk_bf16_f32 v240, v98, v99
	v_cvt_pk_bf16_f32 v241, v100, v101
	global_store_dwordx4 v[116:117], v[238:241], off
	v_or_b32_e32 v99, 48, v181
	v_mad_i64_i32 v[100:101], s[2:3], v99, s59, v[162:163]
	v_lshl_add_u64 v[100:101], v[100:101], 0, v[164:165]
	v_pk_fma_f32 v[94:95], v[94:95], v[248:249], v[78:79] op_sel_hi:[1,0,1]
	v_pk_fma_f32 v[96:97], v[96:97], v[248:249], v[80:81] op_sel_hi:[1,0,1]
	v_pk_fma_f32 v[86:87], v[86:87], v[248:249], v[70:71] op_sel_hi:[1,0,1]
	v_pk_fma_f32 v[88:89], v[88:89], v[248:249], v[72:73] op_sel_hi:[1,0,1]
	v_pk_fma_f32 v[90:91], v[90:91], v[248:249], v[74:75] op_sel_hi:[1,0,1]
	v_pk_fma_f32 v[92:93], v[92:93], v[248:249], v[76:77] op_sel_hi:[1,0,1]
	v_pk_fma_f32 v[82:83], v[82:83], v[248:249], v[66:67] op_sel_hi:[1,0,1]
	v_pk_fma_f32 v[84:85], v[84:85], v[248:249], v[68:69] op_sel_hi:[1,0,1]
	v_pk_mul_f32 v[234:235], v[94:95], s[100:101] op_sel_hi:[1,0]
	v_pk_mul_f32 v[236:237], v[96:97], s[100:101] op_sel_hi:[1,0]
	v_exp_f32_e32 v234, v234
	v_exp_f32_e32 v235, v235
	v_exp_f32_e32 v236, v236
	v_exp_f32_e32 v237, v237
	v_pk_add_f32 v[234:235], v[234:235], 1.0 op_sel_hi:[1,0]
	v_pk_add_f32 v[236:237], v[236:237], 1.0 op_sel_hi:[1,0]
	v_rcp_f32_e32 v234, v234
	v_rcp_f32_e32 v235, v235
	v_rcp_f32_e32 v236, v236
	v_rcp_f32_e32 v237, v237
	v_pk_mul_f32 v[86:87], v[94:95], v[86:87]
	v_pk_mul_f32 v[88:89], v[96:97], v[88:89]
	v_pk_mul_f32 v[86:87], v[86:87], v[234:235]
	v_pk_mul_f32 v[88:89], v[88:89], v[236:237]
	v_cvt_pk_bf16_f32 v238, v86, v87
	v_cvt_pk_bf16_f32 v239, v88, v89
	v_pk_mul_f32 v[234:235], v[90:91], s[100:101] op_sel_hi:[1,0]
; __device__ __forceinline__ unsigned cvt_pk_bf16(float lo, float hi) { unsigned r; asm volatile("v_cvt_pk_bf16_f32 %0, %1, %2" : "=v"(r) : "v"(lo), "v"(hi)); return r; }
; __device__ __forceinline__ float row_rstd(const float* ss, int row) { return 1.0f / sqrtf(ss[row] * (1.0f / DM) + 1e-6f); }
; __device__ __forceinline__ float silu_mul(float a, float b) { return a * b * __builtin_amdgcn_rcpf(1.0f + __builtin_amdgcn_exp2f(-a * LOG2E)); }
;     __device__ __forceinline__ void operator()(const f32x4 (&acc)[2][2][4][2], const Unit& u, int wr, int wc, int fr, int fq) const {
;     ...
;         const float rsl0 = row_rstd(ss, u.pm * BM + wr * 64 + lane), rsl1 = row_rstd(ss, u.pm * BM + HALF + wr * 64 + lane);
; #pragma unroll
;         for (int ai = 0; ai < 2; ++ai)
; #pragma unroll
;             for (int m = 0; m < 4; ++m) { const int row = row0 + ai * HALF + m * 16; const float rs = __shfl(ai ? rsl1 : rsl0, m * 16 + fr); bf16_t* rowp = O + (size_t)row * DFF + col0;
;                 const f32x4 a0 = acc[ai][0][m][0] * rs + ba0, a1 = acc[ai][0][m][1] * rs + ba1, b0 = acc[ai][1][m][0] * rs + bb0, b1 = acc[ai][1][m][1] * rs + bb1;
;                 u32x4 w; w.x = cvt_pk_bf16(silu_mul(a0[0], b0[0]), silu_mul(a0[1], b0[1])); w.y = cvt_pk_bf16(silu_mul(a0[2], b0[2]), silu_mul(a0[3], b0[3]));
;                 w.z = cvt_pk_bf16(silu_mul(a1[0], b1[0]), silu_mul(a1[1], b1[1])); w.w = cvt_pk_bf16(silu_mul(a1[2], b1[2]), silu_mul(a1[3], b1[3]));
;                 *(u32x4*)rowp = w; }
	v_pk_mul_f32 v[236:237], v[92:93], s[100:101] op_sel_hi:[1,0]
	v_exp_f32_e32 v234, v234
	v_exp_f32_e32 v235, v235
	v_exp_f32_e32 v236, v236
	v_exp_f32_e32 v237, v237
	v_pk_add_f32 v[234:235], v[234:235], 1.0 op_sel_hi:[1,0]
	v_pk_add_f32 v[236:237], v[236:237], 1.0 op_sel_hi:[1,0]
	v_rcp_f32_e32 v234, v234
	v_rcp_f32_e32 v235, v235
	v_rcp_f32_e32 v236, v236
	v_rcp_f32_e32 v237, v237
	v_pk_mul_f32 v[82:83], v[90:91], v[82:83]
	v_pk_mul_f32 v[84:85], v[92:93], v[84:85]
	v_pk_mul_f32 v[82:83], v[82:83], v[234:235]
	v_pk_mul_f32 v[84:85], v[84:85], v[236:237]
	v_cvt_pk_bf16_f32 v240, v82, v83
	v_cvt_pk_bf16_f32 v241, v84, v85
	global_store_dwordx4 v[100:101], v[238:241], off
	s_nop 1
	v_div_scale_f32 v82, s[2:3], v182, v182, 1.0
	v_rcp_f32_e32 v84, v82
	v_add_u32_e32 v83, 0x80, v181
	v_fma_f32 v85, -v82, v84, 1.0
	v_fmac_f32_e32 v84, v85, v84
	v_div_scale_f32 v85, vcc, 1.0, v182, 1.0
	v_mul_f32_e32 v86, v85, v84
	v_fma_f32 v87, -v82, v86, v85
	v_fmac_f32_e32 v86, v87, v84
	v_fma_f32 v82, -v82, v86, v85
	v_div_fmas_f32 v82, v82, v84, v86
	v_div_fixup_f32 v82, v82, v182, 1.0
	ds_bpermute_b32 v242, v180, v82
	ds_bpermute_b32 v244, v180, v82 offset:64
	ds_bpermute_b32 v246, v180, v82 offset:128
	ds_bpermute_b32 v248, v180, v82 offset:192
	v_mad_i64_i32 v[86:87], s[2:3], v83, s59, v[162:163]
	v_lshl_add_u64 v[86:87], v[86:87], 0, v[164:165]
	s_andn2_b64 vcc, exec, s[38:39]
	s_waitcnt lgkmcnt(0)
	v_pk_fma_f32 v[62:63], v[62:63], v[242:243], v[78:79] op_sel_hi:[1,0,1]
	v_pk_fma_f32 v[64:65], v[64:65], v[242:243], v[80:81] op_sel_hi:[1,0,1]
	v_pk_fma_f32 v[54:55], v[54:55], v[242:243], v[70:71] op_sel_hi:[1,0,1]
	v_pk_fma_f32 v[56:57], v[56:57], v[242:243], v[72:73] op_sel_hi:[1,0,1]
	v_pk_fma_f32 v[58:59], v[58:59], v[242:243], v[74:75] op_sel_hi:[1,0,1]
	v_pk_fma_f32 v[60:61], v[60:61], v[242:243], v[76:77] op_sel_hi:[1,0,1]
	v_pk_fma_f32 v[50:51], v[50:51], v[242:243], v[66:67] op_sel_hi:[1,0,1]
	v_pk_fma_f32 v[52:53], v[52:53], v[242:243], v[68:69] op_sel_hi:[1,0,1]
	v_pk_mul_f32 v[234:235], v[62:63], s[100:101] op_sel_hi:[1,0]
	v_pk_mul_f32 v[236:237], v[64:65], s[100:101] op_sel_hi:[1,0]
	v_exp_f32_e32 v234, v234
	v_exp_f32_e32 v235, v235
	v_exp_f32_e32 v236, v236
	v_exp_f32_e32 v237, v237
	v_pk_add_f32 v[234:235], v[234:235], 1.0 op_sel_hi:[1,0]
	v_pk_add_f32 v[236:237], v[236:237], 1.0 op_sel_hi:[1,0]
	v_rcp_f32_e32 v234, v234
	v_rcp_f32_e32 v235, v235
	v_rcp_f32_e32 v236, v236
	v_rcp_f32_e32 v237, v237
	v_pk_mul_f32 v[54:55], v[62:63], v[54:55]
	v_pk_mul_f32 v[56:57], v[64:65], v[56:57]
	v_pk_mul_f32 v[54:55], v[54:55], v[234:235]
	v_pk_mul_f32 v[56:57], v[56:57], v[236:237]
	v_cvt_pk_bf16_f32 v238, v54, v55
	v_cvt_pk_bf16_f32 v239, v56, v57
	v_pk_mul_f32 v[234:235], v[58:59], s[100:101] op_sel_hi:[1,0]
	v_pk_mul_f32 v[236:237], v[60:61], s[100:101] op_sel_hi:[1,0]
	v_exp_f32_e32 v234, v234
	v_exp_f32_e32 v235, v235
	v_exp_f32_e32 v236, v236
	v_exp_f32_e32 v237, v237
	v_pk_add_f32 v[234:235], v[234:235], 1.0 op_sel_hi:[1,0]
	v_pk_add_f32 v[236:237], v[236:237], 1.0 op_sel_hi:[1,0]
	v_rcp_f32_e32 v234, v234
	v_rcp_f32_e32 v235, v235
	v_rcp_f32_e32 v236, v236
	v_rcp_f32_e32 v237, v237
	v_pk_mul_f32 v[50:51], v[58:59], v[50:51]
	v_pk_mul_f32 v[52:53], v[60:61], v[52:53]
	v_pk_mul_f32 v[50:51], v[50:51], v[234:235]
	v_pk_mul_f32 v[52:53], v[52:53], v[236:237]
	v_cvt_pk_bf16_f32 v240, v50, v51
	v_cvt_pk_bf16_f32 v241, v52, v53
	global_store_dwordx4 v[86:87], v[238:241], off
	v_add_u32_e32 v51, 0x90, v181
	v_mad_i64_i32 v[52:53], s[2:3], v51, s59, v[162:163]
	v_lshl_add_u64 v[52:53], v[52:53], 0, v[164:165]
	v_pk_fma_f32 v[46:47], v[46:47], v[244:245], v[78:79] op_sel_hi:[1,0,1]
	v_pk_fma_f32 v[48:49], v[48:49], v[244:245], v[80:81] op_sel_hi:[1,0,1]
	v_pk_fma_f32 v[38:39], v[38:39], v[244:245], v[70:71] op_sel_hi:[1,0,1]
	v_pk_fma_f32 v[40:41], v[40:41], v[244:245], v[72:73] op_sel_hi:[1,0,1]
	v_pk_fma_f32 v[42:43], v[42:43], v[244:245], v[74:75] op_sel_hi:[1,0,1]
	v_pk_fma_f32 v[44:45], v[44:45], v[244:245], v[76:77] op_sel_hi:[1,0,1]
	v_pk_fma_f32 v[34:35], v[34:35], v[244:245], v[66:67] op_sel_hi:[1,0,1]
	v_pk_fma_f32 v[36:37], v[36:37], v[244:245], v[68:69] op_sel_hi:[1,0,1]
	v_pk_mul_f32 v[234:235], v[46:47], s[100:101] op_sel_hi:[1,0]
	v_pk_mul_f32 v[236:237], v[48:49], s[100:101] op_sel_hi:[1,0]
	v_exp_f32_e32 v234, v234
	v_exp_f32_e32 v235, v235
	v_exp_f32_e32 v236, v236
	v_exp_f32_e32 v237, v237
	v_pk_add_f32 v[234:235], v[234:235], 1.0 op_sel_hi:[1,0]
	v_pk_add_f32 v[236:237], v[236:237], 1.0 op_sel_hi:[1,0]
	v_rcp_f32_e32 v234, v234
	v_rcp_f32_e32 v235, v235
	v_rcp_f32_e32 v236, v236
	v_rcp_f32_e32 v237, v237
	v_pk_mul_f32 v[38:39], v[46:47], v[38:39]
	v_pk_mul_f32 v[40:41], v[48:49], v[40:41]
	v_pk_mul_f32 v[38:39], v[38:39], v[234:235]
	v_pk_mul_f32 v[40:41], v[40:41], v[236:237]
	v_cvt_pk_bf16_f32 v238, v38, v39
	v_cvt_pk_bf16_f32 v239, v40, v41
	v_pk_mul_f32 v[234:235], v[42:43], s[100:101] op_sel_hi:[1,0]
	v_pk_mul_f32 v[236:237], v[44:45], s[100:101] op_sel_hi:[1,0]
	v_exp_f32_e32 v234, v234
; __device__ __forceinline__ unsigned cvt_pk_bf16(float lo, float hi) { unsigned r; asm volatile("v_cvt_pk_bf16_f32 %0, %1, %2" : "=v"(r) : "v"(lo), "v"(hi)); return r; }
; __device__ __forceinline__ float silu_mul(float a, float b) { return a * b * __builtin_amdgcn_rcpf(1.0f + __builtin_amdgcn_exp2f(-a * LOG2E)); }
; #define PG8_BAR __builtin_amdgcn_s_barrier()
;     __device__ __forceinline__ void operator()(const f32x4 (&acc)[2][2][4][2], const Unit& u, int wr, int wc, int fr, int fq) const {
;     ...
;             for (int m = 0; m < 4; ++m) { const int row = row0 + ai * HALF + m * 16; const float rs = __shfl(ai ? rsl1 : rsl0, m * 16 + fr); bf16_t* rowp = O + (size_t)row * DFF + col0;
;                 const f32x4 a0 = acc[ai][0][m][0] * rs + ba0, a1 = acc[ai][0][m][1] * rs + ba1, b0 = acc[ai][1][m][0] * rs + bb0, b1 = acc[ai][1][m][1] * rs + bb1;
;                 u32x4 w; w.x = cvt_pk_bf16(silu_mul(a0[0], b0[0]), silu_mul(a0[1], b0[1])); w.y = cvt_pk_bf16(silu_mul(a0[2], b0[2]), silu_mul(a0[3], b0[3]));
;                 w.z = cvt_pk_bf16(silu_mul(a1[0], b1[0]), silu_mul(a1[1], b1[1])); w.w = cvt_pk_bf16(silu_mul(a1[2], b1[2]), silu_mul(a1[3], b1[3]));
;                 *(u32x4*)rowp = w; }
; template <class Epi, class Sched, bool ALIGN_EPI = false, bool SP2 = false>
; __device__ __forceinline__ void gemm_phase(LAS unsigned char* lds, const Gemm g, const Sched& S, const Epi& E) {
;     ...
;         if (!has_next) break;
; #pragma unroll
;         for (int a = 0; a < 2; ++a)
; #pragma unroll
;             for (int b = 0; b < 2; ++b)
; #pragma unroll
;                 for (int m = 0; m < 4; ++m)
; #pragma unroll
;                     for (int n = 0; n < 2; ++n) acc[a][b][m][n] = (f32x4){0.f, 0.f, 0.f, 0.f};
;         cur = nxt; cA = nA; cB = nB; ++ui;
;         if constexpr (ALIGN_EPI) { if (wr == 1) PG8_BAR; }
	v_exp_f32_e32 v235, v235
	v_exp_f32_e32 v236, v236
	v_exp_f32_e32 v237, v237
	v_pk_add_f32 v[234:235], v[234:235], 1.0 op_sel_hi:[1,0]
	v_pk_add_f32 v[236:237], v[236:237], 1.0 op_sel_hi:[1,0]
	v_rcp_f32_e32 v234, v234
	v_rcp_f32_e32 v235, v235
	v_rcp_f32_e32 v236, v236
	v_rcp_f32_e32 v237, v237
	v_pk_mul_f32 v[34:35], v[42:43], v[34:35]
	v_pk_mul_f32 v[36:37], v[44:45], v[36:37]
	v_pk_mul_f32 v[34:35], v[34:35], v[234:235]
	v_pk_mul_f32 v[36:37], v[36:37], v[236:237]
	v_cvt_pk_bf16_f32 v240, v34, v35
	v_cvt_pk_bf16_f32 v241, v36, v37
	global_store_dwordx4 v[52:53], v[238:241], off
	v_add_u32_e32 v35, 0xa0, v181
	v_mad_i64_i32 v[36:37], s[2:3], v35, s59, v[162:163]
	v_lshl_add_u64 v[36:37], v[36:37], 0, v[164:165]
	v_pk_fma_f32 v[30:31], v[30:31], v[246:247], v[78:79] op_sel_hi:[1,0,1]
	v_pk_fma_f32 v[32:33], v[32:33], v[246:247], v[80:81] op_sel_hi:[1,0,1]
	v_pk_fma_f32 v[22:23], v[22:23], v[246:247], v[70:71] op_sel_hi:[1,0,1]
	v_pk_fma_f32 v[24:25], v[24:25], v[246:247], v[72:73] op_sel_hi:[1,0,1]
	v_pk_fma_f32 v[26:27], v[26:27], v[246:247], v[74:75] op_sel_hi:[1,0,1]
	v_pk_fma_f32 v[28:29], v[28:29], v[246:247], v[76:77] op_sel_hi:[1,0,1]
	v_pk_fma_f32 v[18:19], v[18:19], v[246:247], v[66:67] op_sel_hi:[1,0,1]
	v_pk_fma_f32 v[20:21], v[20:21], v[246:247], v[68:69] op_sel_hi:[1,0,1]
	v_pk_mul_f32 v[234:235], v[30:31], s[100:101] op_sel_hi:[1,0]
	v_pk_mul_f32 v[236:237], v[32:33], s[100:101] op_sel_hi:[1,0]
	v_exp_f32_e32 v234, v234
	v_exp_f32_e32 v235, v235
	v_exp_f32_e32 v236, v236
	v_exp_f32_e32 v237, v237
	v_pk_add_f32 v[234:235], v[234:235], 1.0 op_sel_hi:[1,0]
	v_pk_add_f32 v[236:237], v[236:237], 1.0 op_sel_hi:[1,0]
	v_rcp_f32_e32 v234, v234
	v_rcp_f32_e32 v235, v235
	v_rcp_f32_e32 v236, v236
	v_rcp_f32_e32 v237, v237
	v_pk_mul_f32 v[22:23], v[30:31], v[22:23]
	v_pk_mul_f32 v[24:25], v[32:33], v[24:25]
	v_pk_mul_f32 v[22:23], v[22:23], v[234:235]
	v_pk_mul_f32 v[24:25], v[24:25], v[236:237]
	v_cvt_pk_bf16_f32 v238, v22, v23
	v_cvt_pk_bf16_f32 v239, v24, v25
	v_pk_mul_f32 v[234:235], v[26:27], s[100:101] op_sel_hi:[1,0]
	v_pk_mul_f32 v[236:237], v[28:29], s[100:101] op_sel_hi:[1,0]
	v_exp_f32_e32 v234, v234
	v_exp_f32_e32 v235, v235
	v_exp_f32_e32 v236, v236
	v_exp_f32_e32 v237, v237
	v_pk_add_f32 v[234:235], v[234:235], 1.0 op_sel_hi:[1,0]
	v_pk_add_f32 v[236:237], v[236:237], 1.0 op_sel_hi:[1,0]
	v_rcp_f32_e32 v234, v234
	v_rcp_f32_e32 v235, v235
	v_rcp_f32_e32 v236, v236
	v_rcp_f32_e32 v237, v237
	v_pk_mul_f32 v[18:19], v[26:27], v[18:19]
	v_pk_mul_f32 v[20:21], v[28:29], v[20:21]
	v_pk_mul_f32 v[18:19], v[18:19], v[234:235]
	v_pk_mul_f32 v[20:21], v[20:21], v[236:237]
	v_cvt_pk_bf16_f32 v240, v18, v19
	v_cvt_pk_bf16_f32 v241, v20, v21
	global_store_dwordx4 v[36:37], v[238:241], off
	v_add_u32_e32 v19, 0xb0, v181
	v_mad_i64_i32 v[20:21], s[2:3], v19, s59, v[162:163]
	v_lshl_add_u64 v[20:21], v[20:21], 0, v[164:165]
	s_mov_b64 s[2:3], -1
	v_pk_fma_f32 v[14:15], v[14:15], v[248:249], v[78:79] op_sel_hi:[1,0,1]
	v_pk_fma_f32 v[16:17], v[16:17], v[248:249], v[80:81] op_sel_hi:[1,0,1]
	v_pk_fma_f32 v[6:7], v[6:7], v[248:249], v[70:71] op_sel_hi:[1,0,1]
	v_pk_fma_f32 v[8:9], v[8:9], v[248:249], v[72:73] op_sel_hi:[1,0,1]
	v_pk_fma_f32 v[10:11], v[10:11], v[248:249], v[74:75] op_sel_hi:[1,0,1]
	v_pk_fma_f32 v[12:13], v[12:13], v[248:249], v[76:77] op_sel_hi:[1,0,1]
	v_pk_fma_f32 v[2:3], v[2:3], v[248:249], v[66:67] op_sel_hi:[1,0,1]
	v_pk_fma_f32 v[4:5], v[4:5], v[248:249], v[68:69] op_sel_hi:[1,0,1]
	v_pk_mul_f32 v[234:235], v[14:15], s[100:101] op_sel_hi:[1,0]
	v_pk_mul_f32 v[236:237], v[16:17], s[100:101] op_sel_hi:[1,0]
	v_exp_f32_e32 v234, v234
	v_exp_f32_e32 v235, v235
	v_exp_f32_e32 v236, v236
	v_exp_f32_e32 v237, v237
	v_pk_add_f32 v[234:235], v[234:235], 1.0 op_sel_hi:[1,0]
	v_pk_add_f32 v[236:237], v[236:237], 1.0 op_sel_hi:[1,0]
	v_rcp_f32_e32 v234, v234
	v_rcp_f32_e32 v235, v235
	v_rcp_f32_e32 v236, v236
	v_rcp_f32_e32 v237, v237
	v_pk_mul_f32 v[6:7], v[14:15], v[6:7]
	v_pk_mul_f32 v[8:9], v[16:17], v[8:9]
	v_pk_mul_f32 v[6:7], v[6:7], v[234:235]
	v_pk_mul_f32 v[8:9], v[8:9], v[236:237]
	v_cvt_pk_bf16_f32 v238, v6, v7
	v_cvt_pk_bf16_f32 v239, v8, v9
	v_pk_mul_f32 v[234:235], v[10:11], s[100:101] op_sel_hi:[1,0]
	v_pk_mul_f32 v[236:237], v[12:13], s[100:101] op_sel_hi:[1,0]
	v_exp_f32_e32 v234, v234
	v_exp_f32_e32 v235, v235
	v_exp_f32_e32 v236, v236
	v_exp_f32_e32 v237, v237
	v_pk_add_f32 v[234:235], v[234:235], 1.0 op_sel_hi:[1,0]
	v_pk_add_f32 v[236:237], v[236:237], 1.0 op_sel_hi:[1,0]
	v_rcp_f32_e32 v234, v234
	v_rcp_f32_e32 v235, v235
	v_rcp_f32_e32 v236, v236
	v_rcp_f32_e32 v237, v237
	v_pk_mul_f32 v[2:3], v[10:11], v[2:3]
	v_pk_mul_f32 v[4:5], v[12:13], v[4:5]
	v_pk_mul_f32 v[2:3], v[2:3], v[234:235]
	v_pk_mul_f32 v[4:5], v[4:5], v[236:237]
	v_cvt_pk_bf16_f32 v240, v2, v3
	v_cvt_pk_bf16_f32 v241, v4, v5
	global_store_dwordx4 v[20:21], v[238:241], off
	s_cbranch_vccnz .LBB0_184
	s_andn2_b64 vcc, exec, s[4:5]
	s_cbranch_vccnz .LBB0_183
	s_barrier
	s_branch .LBB0_183

; __device__ __forceinline__ unsigned cvt_pk_bf16(float lo, float hi) { unsigned r; asm volatile("v_cvt_pk_bf16_f32 %0, %1, %2" : "=v"(r) : "v"(lo), "v"(hi)); return r; }
; __device__ __forceinline__ float silu_mul(float a, float b) { return a * b * __builtin_amdgcn_rcpf(1.0f + __builtin_amdgcn_exp2f(-a * LOG2E)); }
; __device__ __forceinline__ float row_rstd(const float* ss, int row) { return 1.0f / sqrtf(ss[row] * (1.0f / DM) + 1e-6f); }
;     __device__ __forceinline__ void operator()(const f32x4 (&acc)[2][2][4][2], const Unit& u, int wr, int wc, int fr, int fq) const {
;         const int row0 = u.pm * BM + wr * 64 + fr, col0 = u.pn * HALF + wc * 32 + 8 * fq;
;         const int s = (u.pm < ML / BM) ? (u.pm >> 5) : 4;
;         const float* bp = bias + (size_t)s * BIAS_N + u.pn * BM + wc * 32 + 8 * fq;
;         const f32x4 ba0 = *(const f32x4*)bp, ba1 = *(const f32x4*)(bp + 4), bb0 = *(const f32x4*)(bp + HALF), bb1 = *(const f32x4*)(bp + HALF + 4);
;         const int lane = fq * 16 + fr;
;         const float rsl0 = row_rstd(ss, u.pm * BM + wr * 64 + lane), rsl1 = row_rstd(ss, u.pm * BM + HALF + wr * 64 + lane);
; #pragma unroll
;         for (int ai = 0; ai < 2; ++ai)
; #pragma unroll
;             for (int m = 0; m < 4; ++m) { const int row = row0 + ai * HALF + m * 16; const float rs = __shfl(ai ? rsl1 : rsl0, m * 16 + fr); bf16_t* rowp = O + (size_t)row * DFF + col0;
;                 const f32x4 a0 = acc[ai][0][m][0] * rs + ba0, a1 = acc[ai][0][m][1] * rs + ba1, b0 = acc[ai][1][m][0] * rs + bb0, b1 = acc[ai][1][m][1] * rs + bb1;
;                 u32x4 w; w.x = cvt_pk_bf16(silu_mul(a0[0], b0[0]), silu_mul(a0[1], b0[1])); w.y = cvt_pk_bf16(silu_mul(a0[2], b0[2]), silu_mul(a0[3], b0[3]));
;                 w.z = cvt_pk_bf16(silu_mul(a1[0], b1[0]), silu_mul(a1[1], b1[1])); w.w = cvt_pk_bf16(silu_mul(a1[2], b1[2]), silu_mul(a1[3], b1[3]));
;                 *(u32x4*)rowp = w; }
.LBB0_1470:
	s_lshl_b32 s2, s2, 8
	s_add_i32 s13, s2, s42
	s_lshl_b64 s[2:3], s[16:17], 2
	s_add_u32 s15, s43, s2
	s_addc_u32 s16, s44, s3
	s_lshl_b32 s2, s0, 8
	s_ashr_i32 s3, s2, 31
	s_lshl_b64 s[2:3], s[2:3], 2
	v_lshl_or_b32 v164, s0, 7, v173
	s_add_u32 s0, s15, s2
	s_addc_u32 s3, s16, s3
	v_or_b32_e32 v162, s13, v171
	s_add_u32 s2, s0, s50
	v_ashrrev_i32_e32 v163, 31, v162
	s_addc_u32 s3, s3, 0
	v_lshl_add_u64 v[162:163], v[162:163], 2, s[64:65]
	v_mov_b32_e32 v74, v234
	v_mov_b32_e32 v75, v235
	v_mov_b32_e32 v76, v236
	v_mov_b32_e32 v77, v237
	v_mov_b32_e32 v78, v238
	v_mov_b32_e32 v79, v239
	v_mov_b32_e32 v80, v240
	v_mov_b32_e32 v81, v241
	v_mov_b32_e32 v66, v242
	v_mov_b32_e32 v67, v243
	v_mov_b32_e32 v68, v244
	v_mov_b32_e32 v69, v245
	v_mov_b32_e32 v70, v246
	v_mov_b32_e32 v71, v247
	v_mov_b32_e32 v72, v248
	v_mov_b32_e32 v73, v249
	v_or_b32_e32 v181, s13, v169
	v_mov_b32_e32 v162, v250
	s_waitcnt vmcnt(0)
	v_fmamk_f32 v162, v162, 0x3a000000, v178
	v_cmp_gt_f32_e32 vcc, s51, v162
	v_mul_f32_e32 v163, 0x4f800000, v162
	s_nop 0
	v_cndmask_b32_e32 v162, v162, v163, vcc
	v_sqrt_f32_e32 v163, v162
	s_nop 0
	v_add_u32_e32 v165, -1, v163
	v_fma_f32 v166, -v165, v163, v162
	v_cmp_ge_f32_e64 s[2:3], 0, v166
	v_add_u32_e32 v166, 1, v163
	s_nop 0
	v_cndmask_b32_e64 v165, v163, v165, s[2:3]
	v_fma_f32 v163, -v166, v163, v162
	v_cmp_lt_f32_e64 s[2:3], 0, v163
	s_nop 1
	v_cndmask_b32_e64 v163, v165, v166, s[2:3]
	v_mul_f32_e32 v165, 0x37800000, v163
	v_cndmask_b32_e32 v163, v163, v165, vcc
	v_cmp_class_f32_e32 vcc, v162, v179
	s_nop 1
	v_cndmask_b32_e32 v166, v163, v162, vcc
	v_add_u32_e32 v162, s13, v172
	v_ashrrev_i32_e32 v163, 31, v162
	v_lshl_add_u64 v[162:163], v[162:163], 2, s[64:65]
	v_mov_b32_e32 v162, v251
	v_fmamk_f32 v162, v162, 0x3a000000, v178
	v_cmp_gt_f32_e32 vcc, s51, v162
	v_mul_f32_e32 v163, 0x4f800000, v162
	s_nop 0
	v_cndmask_b32_e32 v162, v162, v163, vcc
	v_sqrt_f32_e32 v163, v162
	s_nop 0
	v_add_u32_e32 v165, -1, v163
	v_fma_f32 v167, -v165, v163, v162
	v_cmp_ge_f32_e64 s[2:3], 0, v167
	v_add_u32_e32 v167, 1, v163
	s_nop 0
	v_cndmask_b32_e64 v165, v163, v165, s[2:3]
	v_fma_f32 v163, -v167, v163, v162
	v_cmp_lt_f32_e64 s[2:3], 0, v163
	s_nop 1
	v_cndmask_b32_e64 v163, v165, v167, s[2:3]
	v_mul_f32_e32 v165, 0x37800000, v163
	v_cndmask_b32_e32 v163, v163, v165, vcc
	v_cmp_class_f32_e32 vcc, v162, v179
	v_ashrrev_i32_e32 v165, 31, v164
	v_lshlrev_b64 v[164:165], 1, v[164:165]
	v_cndmask_b32_e32 v182, v163, v162, vcc
	v_div_scale_f32 v162, s[2:3], v166, v166, 1.0
	v_rcp_f32_e32 v163, v162
	s_nop 0
	v_fma_f32 v167, -v162, v163, 1.0
	v_fmac_f32_e32 v163, v167, v163
	v_div_scale_f32 v167, vcc, 1.0, v166, 1.0
	v_mul_f32_e32 v168, v167, v163
	v_fma_f32 v183, -v162, v168, v167
	v_fmac_f32_e32 v168, v183, v163
	v_fma_f32 v162, -v162, v168, v167
	v_div_fmas_f32 v162, v162, v163, v168
	v_div_fixup_f32 v183, v162, v166, 1.0
	s_mov_b32 s100, 0xbfb8aa3b
	ds_bpermute_b32 v242, v180, v183
	ds_bpermute_b32 v244, v180, v183 offset:64
	ds_bpermute_b32 v246, v180, v183 offset:128
	ds_bpermute_b32 v248, v180, v183 offset:192
	v_mov_b64_e32 v[162:163], s[96:97]
	v_mad_i64_i32 v[166:167], s[2:3], v181, s49, v[162:163]
	v_lshl_add_u64 v[166:167], v[166:167], 0, v[164:165]
	s_waitcnt lgkmcnt(0)
	v_pk_fma_f32 v[142:143], v[142:143], v[242:243], v[78:79] op_sel_hi:[1,0,1]
	v_pk_fma_f32 v[144:145], v[144:145], v[242:243], v[80:81] op_sel_hi:[1,0,1]
	v_pk_fma_f32 v[134:135], v[134:135], v[242:243], v[70:71] op_sel_hi:[1,0,1]
	v_pk_fma_f32 v[136:137], v[136:137], v[242:243], v[72:73] op_sel_hi:[1,0,1]
	v_pk_fma_f32 v[138:139], v[138:139], v[242:243], v[74:75] op_sel_hi:[1,0,1]
	v_pk_fma_f32 v[140:141], v[140:141], v[242:243], v[76:77] op_sel_hi:[1,0,1]
	v_pk_fma_f32 v[130:131], v[130:131], v[242:243], v[66:67] op_sel_hi:[1,0,1]
	v_pk_fma_f32 v[132:133], v[132:133], v[242:243], v[68:69] op_sel_hi:[1,0,1]
	v_pk_mul_f32 v[234:235], v[142:143], s[100:101] op_sel_hi:[1,0]
	v_pk_mul_f32 v[236:237], v[144:145], s[100:101] op_sel_hi:[1,0]
	v_exp_f32_e32 v234, v234
	v_exp_f32_e32 v235, v235
	v_exp_f32_e32 v236, v236
	v_exp_f32_e32 v237, v237
	v_pk_add_f32 v[234:235], v[234:235], 1.0 op_sel_hi:[1,0]
	v_pk_add_f32 v[236:237], v[236:237], 1.0 op_sel_hi:[1,0]
	v_rcp_f32_e32 v234, v234
	v_rcp_f32_e32 v235, v235
	v_rcp_f32_e32 v236, v236
	v_rcp_f32_e32 v237, v237
	v_pk_mul_f32 v[134:135], v[142:143], v[134:135]
	v_pk_mul_f32 v[136:137], v[144:145], v[136:137]
	v_pk_mul_f32 v[134:135], v[134:135], v[234:235]
	v_pk_mul_f32 v[136:137], v[136:137], v[236:237]
	v_cvt_pk_bf16_f32 v238, v134, v135
	v_cvt_pk_bf16_f32 v239, v136, v137
	v_pk_mul_f32 v[234:235], v[138:139], s[100:101] op_sel_hi:[1,0]
	v_pk_mul_f32 v[236:237], v[140:141], s[100:101] op_sel_hi:[1,0]
	v_exp_f32_e32 v234, v234
	v_exp_f32_e32 v235, v235
	v_exp_f32_e32 v236, v236
	v_exp_f32_e32 v237, v237
	v_pk_add_f32 v[234:235], v[234:235], 1.0 op_sel_hi:[1,0]
	v_pk_add_f32 v[236:237], v[236:237], 1.0 op_sel_hi:[1,0]
	v_rcp_f32_e32 v234, v234
	v_rcp_f32_e32 v235, v235
	v_rcp_f32_e32 v236, v236
	v_rcp_f32_e32 v237, v237
	v_pk_mul_f32 v[130:131], v[138:139], v[130:131]
	v_pk_mul_f32 v[132:133], v[140:141], v[132:133]
	v_pk_mul_f32 v[130:131], v[130:131], v[234:235]
	v_pk_mul_f32 v[132:133], v[132:133], v[236:237]
	v_cvt_pk_bf16_f32 v240, v130, v131
	v_cvt_pk_bf16_f32 v241, v132, v133
	global_store_dwordx4 v[166:167], v[238:241], off
	v_or_b32_e32 v131, 16, v181
	v_mad_i64_i32 v[132:133], s[2:3], v131, s49, v[162:163]
	v_lshl_add_u64 v[132:133], v[132:133], 0, v[164:165]
	v_pk_fma_f32 v[126:127], v[126:127], v[244:245], v[78:79] op_sel_hi:[1,0,1]
	v_pk_fma_f32 v[128:129], v[128:129], v[244:245], v[80:81] op_sel_hi:[1,0,1]
; __device__ __forceinline__ unsigned cvt_pk_bf16(float lo, float hi) { unsigned r; asm volatile("v_cvt_pk_bf16_f32 %0, %1, %2" : "=v"(r) : "v"(lo), "v"(hi)); return r; }
; __device__ __forceinline__ float row_rstd(const float* ss, int row) { return 1.0f / sqrtf(ss[row] * (1.0f / DM) + 1e-6f); }
; __device__ __forceinline__ float silu_mul(float a, float b) { return a * b * __builtin_amdgcn_rcpf(1.0f + __builtin_amdgcn_exp2f(-a * LOG2E)); }
;     __device__ __forceinline__ void operator()(const f32x4 (&acc)[2][2][4][2], const Unit& u, int wr, int wc, int fr, int fq) const {
;         const int row0 = u.pm * BM + wr * 64 + fr, col0 = u.pn * HALF + wc * 32 + 8 * fq;
;         const int s = (u.pm < ML / BM) ? (u.pm >> 5) : 4;
;         const float* bp = bias + (size_t)s * BIAS_N + u.pn * BM + wc * 32 + 8 * fq;
;         const f32x4 ba0 = *(const f32x4*)bp, ba1 = *(const f32x4*)(bp + 4), bb0 = *(const f32x4*)(bp + HALF), bb1 = *(const f32x4*)(bp + HALF + 4);
;         const int lane = fq * 16 + fr;
;         const float rsl0 = row_rstd(ss, u.pm * BM + wr * 64 + lane), rsl1 = row_rstd(ss, u.pm * BM + HALF + wr * 64 + lane);
; #pragma unroll
;         for (int ai = 0; ai < 2; ++ai)
; #pragma unroll
;             for (int m = 0; m < 4; ++m) { const int row = row0 + ai * HALF + m * 16; const float rs = __shfl(ai ? rsl1 : rsl0, m * 16 + fr); bf16_t* rowp = O + (size_t)row * DFF + col0;
;                 const f32x4 a0 = acc[ai][0][m][0] * rs + ba0, a1 = acc[ai][0][m][1] * rs + ba1, b0 = acc[ai][1][m][0] * rs + bb0, b1 = acc[ai][1][m][1] * rs + bb1;
;                 u32x4 w; w.x = cvt_pk_bf16(silu_mul(a0[0], b0[0]), silu_mul(a0[1], b0[1])); w.y = cvt_pk_bf16(silu_mul(a0[2], b0[2]), silu_mul(a0[3], b0[3]));
;                 w.z = cvt_pk_bf16(silu_mul(a1[0], b1[0]), silu_mul(a1[1], b1[1])); w.w = cvt_pk_bf16(silu_mul(a1[2], b1[2]), silu_mul(a1[3], b1[3]));
;                 *(u32x4*)rowp = w; }
	v_pk_fma_f32 v[118:119], v[118:119], v[244:245], v[70:71] op_sel_hi:[1,0,1]
	v_pk_fma_f32 v[120:121], v[120:121], v[244:245], v[72:73] op_sel_hi:[1,0,1]
	v_pk_fma_f32 v[122:123], v[122:123], v[244:245], v[74:75] op_sel_hi:[1,0,1]
	v_pk_fma_f32 v[124:125], v[124:125], v[244:245], v[76:77] op_sel_hi:[1,0,1]
	v_pk_fma_f32 v[114:115], v[114:115], v[244:245], v[66:67] op_sel_hi:[1,0,1]
	v_pk_fma_f32 v[116:117], v[116:117], v[244:245], v[68:69] op_sel_hi:[1,0,1]
	v_pk_mul_f32 v[234:235], v[126:127], s[100:101] op_sel_hi:[1,0]
	v_pk_mul_f32 v[236:237], v[128:129], s[100:101] op_sel_hi:[1,0]
	v_exp_f32_e32 v234, v234
	v_exp_f32_e32 v235, v235
	v_exp_f32_e32 v236, v236
	v_exp_f32_e32 v237, v237
	v_pk_add_f32 v[234:235], v[234:235], 1.0 op_sel_hi:[1,0]
	v_pk_add_f32 v[236:237], v[236:237], 1.0 op_sel_hi:[1,0]
	v_rcp_f32_e32 v234, v234
	v_rcp_f32_e32 v235, v235
	v_rcp_f32_e32 v236, v236
	v_rcp_f32_e32 v237, v237
	v_pk_mul_f32 v[118:119], v[126:127], v[118:119]
	v_pk_mul_f32 v[120:121], v[128:129], v[120:121]
	v_pk_mul_f32 v[118:119], v[118:119], v[234:235]
	v_pk_mul_f32 v[120:121], v[120:121], v[236:237]
	v_cvt_pk_bf16_f32 v238, v118, v119
	v_cvt_pk_bf16_f32 v239, v120, v121
	v_pk_mul_f32 v[234:235], v[122:123], s[100:101] op_sel_hi:[1,0]
	v_pk_mul_f32 v[236:237], v[124:125], s[100:101] op_sel_hi:[1,0]
	v_exp_f32_e32 v234, v234
	v_exp_f32_e32 v235, v235
	v_exp_f32_e32 v236, v236
	v_exp_f32_e32 v237, v237
	v_pk_add_f32 v[234:235], v[234:235], 1.0 op_sel_hi:[1,0]
	v_pk_add_f32 v[236:237], v[236:237], 1.0 op_sel_hi:[1,0]
	v_rcp_f32_e32 v234, v234
	v_rcp_f32_e32 v235, v235
	v_rcp_f32_e32 v236, v236
	v_rcp_f32_e32 v237, v237
	v_pk_mul_f32 v[114:115], v[122:123], v[114:115]
	v_pk_mul_f32 v[116:117], v[124:125], v[116:117]
	v_pk_mul_f32 v[114:115], v[114:115], v[234:235]
	v_pk_mul_f32 v[116:117], v[116:117], v[236:237]
	v_cvt_pk_bf16_f32 v240, v114, v115
	v_cvt_pk_bf16_f32 v241, v116, v117
	global_store_dwordx4 v[132:133], v[238:241], off
	v_or_b32_e32 v115, 32, v181
	v_mad_i64_i32 v[116:117], s[2:3], v115, s49, v[162:163]
	v_lshl_add_u64 v[116:117], v[116:117], 0, v[164:165]
	v_pk_fma_f32 v[110:111], v[110:111], v[246:247], v[78:79] op_sel_hi:[1,0,1]
	v_pk_fma_f32 v[112:113], v[112:113], v[246:247], v[80:81] op_sel_hi:[1,0,1]
	v_pk_fma_f32 v[102:103], v[102:103], v[246:247], v[70:71] op_sel_hi:[1,0,1]
	v_pk_fma_f32 v[104:105], v[104:105], v[246:247], v[72:73] op_sel_hi:[1,0,1]
	v_pk_fma_f32 v[106:107], v[106:107], v[246:247], v[74:75] op_sel_hi:[1,0,1]
	v_pk_fma_f32 v[108:109], v[108:109], v[246:247], v[76:77] op_sel_hi:[1,0,1]
	v_pk_fma_f32 v[98:99], v[98:99], v[246:247], v[66:67] op_sel_hi:[1,0,1]
	v_pk_fma_f32 v[100:101], v[100:101], v[246:247], v[68:69] op_sel_hi:[1,0,1]
	v_pk_mul_f32 v[234:235], v[110:111], s[100:101] op_sel_hi:[1,0]
	v_pk_mul_f32 v[236:237], v[112:113], s[100:101] op_sel_hi:[1,0]
	v_exp_f32_e32 v234, v234
	v_exp_f32_e32 v235, v235
	v_exp_f32_e32 v236, v236
	v_exp_f32_e32 v237, v237
	v_pk_add_f32 v[234:235], v[234:235], 1.0 op_sel_hi:[1,0]
	v_pk_add_f32 v[236:237], v[236:237], 1.0 op_sel_hi:[1,0]
	v_rcp_f32_e32 v234, v234
	v_rcp_f32_e32 v235, v235
	v_rcp_f32_e32 v236, v236
	v_rcp_f32_e32 v237, v237
	v_pk_mul_f32 v[102:103], v[110:111], v[102:103]
	v_pk_mul_f32 v[104:105], v[112:113], v[104:105]
	v_pk_mul_f32 v[102:103], v[102:103], v[234:235]
	v_pk_mul_f32 v[104:105], v[104:105], v[236:237]
	v_cvt_pk_bf16_f32 v238, v102, v103
	v_cvt_pk_bf16_f32 v239, v104, v105
	v_pk_mul_f32 v[234:235], v[106:107], s[100:101] op_sel_hi:[1,0]
	v_pk_mul_f32 v[236:237], v[108:109], s[100:101] op_sel_hi:[1,0]
	v_exp_f32_e32 v234, v234
	v_exp_f32_e32 v235, v235
	v_exp_f32_e32 v236, v236
	v_exp_f32_e32 v237, v237
	v_pk_add_f32 v[234:235], v[234:235], 1.0 op_sel_hi:[1,0]
	v_pk_add_f32 v[236:237], v[236:237], 1.0 op_sel_hi:[1,0]
	v_rcp_f32_e32 v234, v234
	v_rcp_f32_e32 v235, v235
	v_rcp_f32_e32 v236, v236
	v_rcp_f32_e32 v237, v237
	v_pk_mul_f32 v[98:99], v[106:107], v[98:99]
	v_pk_mul_f32 v[100:101], v[108:109], v[100:101]
	v_pk_mul_f32 v[98:99], v[98:99], v[234:235]
	v_pk_mul_f32 v[100:101], v[100:101], v[236:237]
	v_cvt_pk_bf16_f32 v240, v98, v99
	v_cvt_pk_bf16_f32 v241, v100, v101
	global_store_dwordx4 v[116:117], v[238:241], off
	v_or_b32_e32 v99, 48, v181
	v_mad_i64_i32 v[100:101], s[2:3], v99, s49, v[162:163]
	v_lshl_add_u64 v[100:101], v[100:101], 0, v[164:165]
	v_pk_fma_f32 v[94:95], v[94:95], v[248:249], v[78:79] op_sel_hi:[1,0,1]
	v_pk_fma_f32 v[96:97], v[96:97], v[248:249], v[80:81] op_sel_hi:[1,0,1]
	v_pk_fma_f32 v[86:87], v[86:87], v[248:249], v[70:71] op_sel_hi:[1,0,1]
	v_pk_fma_f32 v[88:89], v[88:89], v[248:249], v[72:73] op_sel_hi:[1,0,1]
	v_pk_fma_f32 v[90:91], v[90:91], v[248:249], v[74:75] op_sel_hi:[1,0,1]
	v_pk_fma_f32 v[92:93], v[92:93], v[248:249], v[76:77] op_sel_hi:[1,0,1]
	v_pk_fma_f32 v[82:83], v[82:83], v[248:249], v[66:67] op_sel_hi:[1,0,1]
	v_pk_fma_f32 v[84:85], v[84:85], v[248:249], v[68:69] op_sel_hi:[1,0,1]
	v_pk_mul_f32 v[234:235], v[94:95], s[100:101] op_sel_hi:[1,0]
	v_pk_mul_f32 v[236:237], v[96:97], s[100:101] op_sel_hi:[1,0]
	v_exp_f32_e32 v234, v234
	v_exp_f32_e32 v235, v235
	v_exp_f32_e32 v236, v236
	v_exp_f32_e32 v237, v237
	v_pk_add_f32 v[234:235], v[234:235], 1.0 op_sel_hi:[1,0]
	v_pk_add_f32 v[236:237], v[236:237], 1.0 op_sel_hi:[1,0]
	v_rcp_f32_e32 v234, v234
	v_rcp_f32_e32 v235, v235
	v_rcp_f32_e32 v236, v236
	v_rcp_f32_e32 v237, v237
	v_pk_mul_f32 v[86:87], v[94:95], v[86:87]
	v_pk_mul_f32 v[88:89], v[96:97], v[88:89]
	v_pk_mul_f32 v[86:87], v[86:87], v[234:235]
	v_pk_mul_f32 v[88:89], v[88:89], v[236:237]
	v_cvt_pk_bf16_f32 v238, v86, v87
	v_cvt_pk_bf16_f32 v239, v88, v89
	v_pk_mul_f32 v[234:235], v[90:91], s[100:101] op_sel_hi:[1,0]
; __device__ __forceinline__ unsigned cvt_pk_bf16(float lo, float hi) { unsigned r; asm volatile("v_cvt_pk_bf16_f32 %0, %1, %2" : "=v"(r) : "v"(lo), "v"(hi)); return r; }
; __device__ __forceinline__ float row_rstd(const float* ss, int row) { return 1.0f / sqrtf(ss[row] * (1.0f / DM) + 1e-6f); }
; __device__ __forceinline__ float silu_mul(float a, float b) { return a * b * __builtin_amdgcn_rcpf(1.0f + __builtin_amdgcn_exp2f(-a * LOG2E)); }
;     __device__ __forceinline__ void operator()(const f32x4 (&acc)[2][2][4][2], const Unit& u, int wr, int wc, int fr, int fq) const {
;     ...
;         const float rsl0 = row_rstd(ss, u.pm * BM + wr * 64 + lane), rsl1 = row_rstd(ss, u.pm * BM + HALF + wr * 64 + lane);
; #pragma unroll
;         for (int ai = 0; ai < 2; ++ai)
; #pragma unroll
;             for (int m = 0; m < 4; ++m) { const int row = row0 + ai * HALF + m * 16; const float rs = __shfl(ai ? rsl1 : rsl0, m * 16 + fr); bf16_t* rowp = O + (size_t)row * DFF + col0;
;                 const f32x4 a0 = acc[ai][0][m][0] * rs + ba0, a1 = acc[ai][0][m][1] * rs + ba1, b0 = acc[ai][1][m][0] * rs + bb0, b1 = acc[ai][1][m][1] * rs + bb1;
;                 u32x4 w; w.x = cvt_pk_bf16(silu_mul(a0[0], b0[0]), silu_mul(a0[1], b0[1])); w.y = cvt_pk_bf16(silu_mul(a0[2], b0[2]), silu_mul(a0[3], b0[3]));
;                 w.z = cvt_pk_bf16(silu_mul(a1[0], b1[0]), silu_mul(a1[1], b1[1])); w.w = cvt_pk_bf16(silu_mul(a1[2], b1[2]), silu_mul(a1[3], b1[3]));
;                 *(u32x4*)rowp = w; }
	v_pk_mul_f32 v[236:237], v[92:93], s[100:101] op_sel_hi:[1,0]
	v_exp_f32_e32 v234, v234
	v_exp_f32_e32 v235, v235
	v_exp_f32_e32 v236, v236
	v_exp_f32_e32 v237, v237
	v_pk_add_f32 v[234:235], v[234:235], 1.0 op_sel_hi:[1,0]
	v_pk_add_f32 v[236:237], v[236:237], 1.0 op_sel_hi:[1,0]
	v_rcp_f32_e32 v234, v234
	v_rcp_f32_e32 v235, v235
	v_rcp_f32_e32 v236, v236
	v_rcp_f32_e32 v237, v237
	v_pk_mul_f32 v[82:83], v[90:91], v[82:83]
	v_pk_mul_f32 v[84:85], v[92:93], v[84:85]
	v_pk_mul_f32 v[82:83], v[82:83], v[234:235]
	v_pk_mul_f32 v[84:85], v[84:85], v[236:237]
	v_cvt_pk_bf16_f32 v240, v82, v83
	v_cvt_pk_bf16_f32 v241, v84, v85
	global_store_dwordx4 v[100:101], v[238:241], off
	s_nop 1
	v_div_scale_f32 v82, s[2:3], v182, v182, 1.0
	v_rcp_f32_e32 v84, v82
	v_add_u32_e32 v83, 0x80, v181
	v_fma_f32 v85, -v82, v84, 1.0
	v_fmac_f32_e32 v84, v85, v84
	v_div_scale_f32 v85, vcc, 1.0, v182, 1.0
	v_mul_f32_e32 v86, v85, v84
	v_fma_f32 v87, -v82, v86, v85
	v_fmac_f32_e32 v86, v87, v84
	v_fma_f32 v82, -v82, v86, v85
	v_div_fmas_f32 v82, v82, v84, v86
	v_div_fixup_f32 v82, v82, v182, 1.0
	ds_bpermute_b32 v242, v180, v82
	ds_bpermute_b32 v244, v180, v82 offset:64
	ds_bpermute_b32 v246, v180, v82 offset:128
	ds_bpermute_b32 v248, v180, v82 offset:192
	v_mad_i64_i32 v[86:87], s[2:3], v83, s49, v[162:163]
	v_lshl_add_u64 v[86:87], v[86:87], 0, v[164:165]
	s_andn2_b64 vcc, exec, s[38:39]
	s_waitcnt lgkmcnt(0)
	v_pk_fma_f32 v[62:63], v[62:63], v[242:243], v[78:79] op_sel_hi:[1,0,1]
	v_pk_fma_f32 v[64:65], v[64:65], v[242:243], v[80:81] op_sel_hi:[1,0,1]
	v_pk_fma_f32 v[54:55], v[54:55], v[242:243], v[70:71] op_sel_hi:[1,0,1]
	v_pk_fma_f32 v[56:57], v[56:57], v[242:243], v[72:73] op_sel_hi:[1,0,1]
	v_pk_fma_f32 v[58:59], v[58:59], v[242:243], v[74:75] op_sel_hi:[1,0,1]
	v_pk_fma_f32 v[60:61], v[60:61], v[242:243], v[76:77] op_sel_hi:[1,0,1]
	v_pk_fma_f32 v[50:51], v[50:51], v[242:243], v[66:67] op_sel_hi:[1,0,1]
	v_pk_fma_f32 v[52:53], v[52:53], v[242:243], v[68:69] op_sel_hi:[1,0,1]
	v_pk_mul_f32 v[234:235], v[62:63], s[100:101] op_sel_hi:[1,0]
	v_pk_mul_f32 v[236:237], v[64:65], s[100:101] op_sel_hi:[1,0]
	v_exp_f32_e32 v234, v234
	v_exp_f32_e32 v235, v235
	v_exp_f32_e32 v236, v236
	v_exp_f32_e32 v237, v237
	v_pk_add_f32 v[234:235], v[234:235], 1.0 op_sel_hi:[1,0]
	v_pk_add_f32 v[236:237], v[236:237], 1.0 op_sel_hi:[1,0]
	v_rcp_f32_e32 v234, v234
	v_rcp_f32_e32 v235, v235
	v_rcp_f32_e32 v236, v236
	v_rcp_f32_e32 v237, v237
	v_pk_mul_f32 v[54:55], v[62:63], v[54:55]
	v_pk_mul_f32 v[56:57], v[64:65], v[56:57]
	v_pk_mul_f32 v[54:55], v[54:55], v[234:235]
	v_pk_mul_f32 v[56:57], v[56:57], v[236:237]
	v_cvt_pk_bf16_f32 v238, v54, v55
	v_cvt_pk_bf16_f32 v239, v56, v57
	v_pk_mul_f32 v[234:235], v[58:59], s[100:101] op_sel_hi:[1,0]
	v_pk_mul_f32 v[236:237], v[60:61], s[100:101] op_sel_hi:[1,0]
	v_exp_f32_e32 v234, v234
	v_exp_f32_e32 v235, v235
	v_exp_f32_e32 v236, v236
	v_exp_f32_e32 v237, v237
	v_pk_add_f32 v[234:235], v[234:235], 1.0 op_sel_hi:[1,0]
	v_pk_add_f32 v[236:237], v[236:237], 1.0 op_sel_hi:[1,0]
	v_rcp_f32_e32 v234, v234
	v_rcp_f32_e32 v235, v235
	v_rcp_f32_e32 v236, v236
	v_rcp_f32_e32 v237, v237
	v_pk_mul_f32 v[50:51], v[58:59], v[50:51]
	v_pk_mul_f32 v[52:53], v[60:61], v[52:53]
	v_pk_mul_f32 v[50:51], v[50:51], v[234:235]
	v_pk_mul_f32 v[52:53], v[52:53], v[236:237]
	v_cvt_pk_bf16_f32 v240, v50, v51
	v_cvt_pk_bf16_f32 v241, v52, v53
	global_store_dwordx4 v[86:87], v[238:241], off
	v_add_u32_e32 v51, 0x90, v181
	v_mad_i64_i32 v[52:53], s[2:3], v51, s49, v[162:163]
	v_lshl_add_u64 v[52:53], v[52:53], 0, v[164:165]
	v_pk_fma_f32 v[46:47], v[46:47], v[244:245], v[78:79] op_sel_hi:[1,0,1]
	v_pk_fma_f32 v[48:49], v[48:49], v[244:245], v[80:81] op_sel_hi:[1,0,1]
	v_pk_fma_f32 v[38:39], v[38:39], v[244:245], v[70:71] op_sel_hi:[1,0,1]
	v_pk_fma_f32 v[40:41], v[40:41], v[244:245], v[72:73] op_sel_hi:[1,0,1]
	v_pk_fma_f32 v[42:43], v[42:43], v[244:245], v[74:75] op_sel_hi:[1,0,1]
	v_pk_fma_f32 v[44:45], v[44:45], v[244:245], v[76:77] op_sel_hi:[1,0,1]
	v_pk_fma_f32 v[34:35], v[34:35], v[244:245], v[66:67] op_sel_hi:[1,0,1]
	v_pk_fma_f32 v[36:37], v[36:37], v[244:245], v[68:69] op_sel_hi:[1,0,1]
	v_pk_mul_f32 v[234:235], v[46:47], s[100:101] op_sel_hi:[1,0]
	v_pk_mul_f32 v[236:237], v[48:49], s[100:101] op_sel_hi:[1,0]
	v_exp_f32_e32 v234, v234
	v_exp_f32_e32 v235, v235
	v_exp_f32_e32 v236, v236
	v_exp_f32_e32 v237, v237
	v_pk_add_f32 v[234:235], v[234:235], 1.0 op_sel_hi:[1,0]
	v_pk_add_f32 v[236:237], v[236:237], 1.0 op_sel_hi:[1,0]
	v_rcp_f32_e32 v234, v234
	v_rcp_f32_e32 v235, v235
	v_rcp_f32_e32 v236, v236
	v_rcp_f32_e32 v237, v237
	v_pk_mul_f32 v[38:39], v[46:47], v[38:39]
	v_pk_mul_f32 v[40:41], v[48:49], v[40:41]
	v_pk_mul_f32 v[38:39], v[38:39], v[234:235]
	v_pk_mul_f32 v[40:41], v[40:41], v[236:237]
	v_cvt_pk_bf16_f32 v238, v38, v39
	v_cvt_pk_bf16_f32 v239, v40, v41
	v_pk_mul_f32 v[234:235], v[42:43], s[100:101] op_sel_hi:[1,0]
	v_pk_mul_f32 v[236:237], v[44:45], s[100:101] op_sel_hi:[1,0]
	v_exp_f32_e32 v234, v234
; __device__ __forceinline__ unsigned cvt_pk_bf16(float lo, float hi) { unsigned r; asm volatile("v_cvt_pk_bf16_f32 %0, %1, %2" : "=v"(r) : "v"(lo), "v"(hi)); return r; }
; __device__ __forceinline__ float silu_mul(float a, float b) { return a * b * __builtin_amdgcn_rcpf(1.0f + __builtin_amdgcn_exp2f(-a * LOG2E)); }
; #define PG8_BAR __builtin_amdgcn_s_barrier()
;     __device__ __forceinline__ void operator()(const f32x4 (&acc)[2][2][4][2], const Unit& u, int wr, int wc, int fr, int fq) const {
;     ...
;             for (int m = 0; m < 4; ++m) { const int row = row0 + ai * HALF + m * 16; const float rs = __shfl(ai ? rsl1 : rsl0, m * 16 + fr); bf16_t* rowp = O + (size_t)row * DFF + col0;
;                 const f32x4 a0 = acc[ai][0][m][0] * rs + ba0, a1 = acc[ai][0][m][1] * rs + ba1, b0 = acc[ai][1][m][0] * rs + bb0, b1 = acc[ai][1][m][1] * rs + bb1;
;                 u32x4 w; w.x = cvt_pk_bf16(silu_mul(a0[0], b0[0]), silu_mul(a0[1], b0[1])); w.y = cvt_pk_bf16(silu_mul(a0[2], b0[2]), silu_mul(a0[3], b0[3]));
;                 w.z = cvt_pk_bf16(silu_mul(a1[0], b1[0]), silu_mul(a1[1], b1[1])); w.w = cvt_pk_bf16(silu_mul(a1[2], b1[2]), silu_mul(a1[3], b1[3]));
;                 *(u32x4*)rowp = w; }
; template <class Epi, class Sched, bool ALIGN_EPI = false, bool SP2 = false>
; __device__ __forceinline__ void gemm_phase(LAS unsigned char* lds, const Gemm g, const Sched& S, const Epi& E) {
;     ...
;         if (!has_next) break;
; #pragma unroll
;         for (int a = 0; a < 2; ++a)
; #pragma unroll
;             for (int b = 0; b < 2; ++b)
; #pragma unroll
;                 for (int m = 0; m < 4; ++m)
; #pragma unroll
;                     for (int n = 0; n < 2; ++n) acc[a][b][m][n] = (f32x4){0.f, 0.f, 0.f, 0.f};
;         cur = nxt; cA = nA; cB = nB; ++ui;
;         if constexpr (ALIGN_EPI) { if (wr == 1) PG8_BAR; }
	v_exp_f32_e32 v235, v235
	v_exp_f32_e32 v236, v236
	v_exp_f32_e32 v237, v237
	v_pk_add_f32 v[234:235], v[234:235], 1.0 op_sel_hi:[1,0]
	v_pk_add_f32 v[236:237], v[236:237], 1.0 op_sel_hi:[1,0]
	v_rcp_f32_e32 v234, v234
	v_rcp_f32_e32 v235, v235
	v_rcp_f32_e32 v236, v236
	v_rcp_f32_e32 v237, v237
	v_pk_mul_f32 v[34:35], v[42:43], v[34:35]
	v_pk_mul_f32 v[36:37], v[44:45], v[36:37]
	v_pk_mul_f32 v[34:35], v[34:35], v[234:235]
	v_pk_mul_f32 v[36:37], v[36:37], v[236:237]
	v_cvt_pk_bf16_f32 v240, v34, v35
	v_cvt_pk_bf16_f32 v241, v36, v37
	global_store_dwordx4 v[52:53], v[238:241], off
	v_add_u32_e32 v35, 0xa0, v181
	v_mad_i64_i32 v[36:37], s[2:3], v35, s49, v[162:163]
	v_lshl_add_u64 v[36:37], v[36:37], 0, v[164:165]
	v_pk_fma_f32 v[30:31], v[30:31], v[246:247], v[78:79] op_sel_hi:[1,0,1]
	v_pk_fma_f32 v[32:33], v[32:33], v[246:247], v[80:81] op_sel_hi:[1,0,1]
	v_pk_fma_f32 v[22:23], v[22:23], v[246:247], v[70:71] op_sel_hi:[1,0,1]
	v_pk_fma_f32 v[24:25], v[24:25], v[246:247], v[72:73] op_sel_hi:[1,0,1]
	v_pk_fma_f32 v[26:27], v[26:27], v[246:247], v[74:75] op_sel_hi:[1,0,1]
	v_pk_fma_f32 v[28:29], v[28:29], v[246:247], v[76:77] op_sel_hi:[1,0,1]
	v_pk_fma_f32 v[18:19], v[18:19], v[246:247], v[66:67] op_sel_hi:[1,0,1]
	v_pk_fma_f32 v[20:21], v[20:21], v[246:247], v[68:69] op_sel_hi:[1,0,1]
	v_pk_mul_f32 v[234:235], v[30:31], s[100:101] op_sel_hi:[1,0]
	v_pk_mul_f32 v[236:237], v[32:33], s[100:101] op_sel_hi:[1,0]
	v_exp_f32_e32 v234, v234
	v_exp_f32_e32 v235, v235
	v_exp_f32_e32 v236, v236
	v_exp_f32_e32 v237, v237
	v_pk_add_f32 v[234:235], v[234:235], 1.0 op_sel_hi:[1,0]
	v_pk_add_f32 v[236:237], v[236:237], 1.0 op_sel_hi:[1,0]
	v_rcp_f32_e32 v234, v234
	v_rcp_f32_e32 v235, v235
	v_rcp_f32_e32 v236, v236
	v_rcp_f32_e32 v237, v237
	v_pk_mul_f32 v[22:23], v[30:31], v[22:23]
	v_pk_mul_f32 v[24:25], v[32:33], v[24:25]
	v_pk_mul_f32 v[22:23], v[22:23], v[234:235]
	v_pk_mul_f32 v[24:25], v[24:25], v[236:237]
	v_cvt_pk_bf16_f32 v238, v22, v23
	v_cvt_pk_bf16_f32 v239, v24, v25
	v_pk_mul_f32 v[234:235], v[26:27], s[100:101] op_sel_hi:[1,0]
	v_pk_mul_f32 v[236:237], v[28:29], s[100:101] op_sel_hi:[1,0]
	v_exp_f32_e32 v234, v234
	v_exp_f32_e32 v235, v235
	v_exp_f32_e32 v236, v236
	v_exp_f32_e32 v237, v237
	v_pk_add_f32 v[234:235], v[234:235], 1.0 op_sel_hi:[1,0]
	v_pk_add_f32 v[236:237], v[236:237], 1.0 op_sel_hi:[1,0]
	v_rcp_f32_e32 v234, v234
	v_rcp_f32_e32 v235, v235
	v_rcp_f32_e32 v236, v236
	v_rcp_f32_e32 v237, v237
	v_pk_mul_f32 v[18:19], v[26:27], v[18:19]
	v_pk_mul_f32 v[20:21], v[28:29], v[20:21]
	v_pk_mul_f32 v[18:19], v[18:19], v[234:235]
	v_pk_mul_f32 v[20:21], v[20:21], v[236:237]
	v_cvt_pk_bf16_f32 v240, v18, v19
	v_cvt_pk_bf16_f32 v241, v20, v21
	global_store_dwordx4 v[36:37], v[238:241], off
	v_add_u32_e32 v19, 0xb0, v181
	v_mad_i64_i32 v[20:21], s[2:3], v19, s49, v[162:163]
	v_lshl_add_u64 v[20:21], v[20:21], 0, v[164:165]
	s_mov_b64 s[2:3], -1
	v_pk_fma_f32 v[14:15], v[14:15], v[248:249], v[78:79] op_sel_hi:[1,0,1]
	v_pk_fma_f32 v[16:17], v[16:17], v[248:249], v[80:81] op_sel_hi:[1,0,1]
	v_pk_fma_f32 v[6:7], v[6:7], v[248:249], v[70:71] op_sel_hi:[1,0,1]
	v_pk_fma_f32 v[8:9], v[8:9], v[248:249], v[72:73] op_sel_hi:[1,0,1]
	v_pk_fma_f32 v[10:11], v[10:11], v[248:249], v[74:75] op_sel_hi:[1,0,1]
	v_pk_fma_f32 v[12:13], v[12:13], v[248:249], v[76:77] op_sel_hi:[1,0,1]
	v_pk_fma_f32 v[2:3], v[2:3], v[248:249], v[66:67] op_sel_hi:[1,0,1]
	v_pk_fma_f32 v[4:5], v[4:5], v[248:249], v[68:69] op_sel_hi:[1,0,1]
	v_pk_mul_f32 v[234:235], v[14:15], s[100:101] op_sel_hi:[1,0]
	v_pk_mul_f32 v[236:237], v[16:17], s[100:101] op_sel_hi:[1,0]
	v_exp_f32_e32 v234, v234
	v_exp_f32_e32 v235, v235
	v_exp_f32_e32 v236, v236
	v_exp_f32_e32 v237, v237
	v_pk_add_f32 v[234:235], v[234:235], 1.0 op_sel_hi:[1,0]
	v_pk_add_f32 v[236:237], v[236:237], 1.0 op_sel_hi:[1,0]
	v_rcp_f32_e32 v234, v234
	v_rcp_f32_e32 v235, v235
	v_rcp_f32_e32 v236, v236
	v_rcp_f32_e32 v237, v237
	v_pk_mul_f32 v[6:7], v[14:15], v[6:7]
	v_pk_mul_f32 v[8:9], v[16:17], v[8:9]
	v_pk_mul_f32 v[6:7], v[6:7], v[234:235]
	v_pk_mul_f32 v[8:9], v[8:9], v[236:237]
	v_cvt_pk_bf16_f32 v238, v6, v7
	v_cvt_pk_bf16_f32 v239, v8, v9
	v_pk_mul_f32 v[234:235], v[10:11], s[100:101] op_sel_hi:[1,0]
	v_pk_mul_f32 v[236:237], v[12:13], s[100:101] op_sel_hi:[1,0]
	v_exp_f32_e32 v234, v234
	v_exp_f32_e32 v235, v235
	v_exp_f32_e32 v236, v236
	v_exp_f32_e32 v237, v237
	v_pk_add_f32 v[234:235], v[234:235], 1.0 op_sel_hi:[1,0]
	v_pk_add_f32 v[236:237], v[236:237], 1.0 op_sel_hi:[1,0]
	v_rcp_f32_e32 v234, v234
	v_rcp_f32_e32 v235, v235
	v_rcp_f32_e32 v236, v236
	v_rcp_f32_e32 v237, v237
	v_pk_mul_f32 v[2:3], v[10:11], v[2:3]
	v_pk_mul_f32 v[4:5], v[12:13], v[4:5]
	v_pk_mul_f32 v[2:3], v[2:3], v[234:235]
	v_pk_mul_f32 v[4:5], v[4:5], v[236:237]
	v_cvt_pk_bf16_f32 v240, v2, v3
	v_cvt_pk_bf16_f32 v241, v4, v5
	global_store_dwordx4 v[20:21], v[238:241], off
	s_cbranch_vccnz .LBB0_1461
	s_andn2_b64 vcc, exec, s[4:5]
	s_cbranch_vccnz .LBB0_1460
	s_barrier
	s_branch .LBB0_1460

; __device__ __forceinline__ unsigned cvt_pk_bf16(float lo, float hi) { unsigned r; asm volatile("v_cvt_pk_bf16_f32 %0, %1, %2" : "=v"(r) : "v"(lo), "v"(hi)); return r; }
; __device__ __forceinline__ float silu_mul(float a, float b) { return a * b * __builtin_amdgcn_rcpf(1.0f + __builtin_amdgcn_exp2f(-a * LOG2E)); }
; __device__ __forceinline__ float row_rstd(const float* ss, int row) { return 1.0f / sqrtf(ss[row] * (1.0f / DM) + 1e-6f); }
;     __device__ __forceinline__ void operator()(const f32x4 (&acc)[2][2][4][2], const Unit& u, int wr, int wc, int fr, int fq) const {
;         const int row0 = u.pm * BM + wr * 64 + fr, col0 = u.pn * HALF + wc * 32 + 8 * fq;
;         const int s = (u.pm < ML / BM) ? (u.pm >> 5) : 4;
;         const float* bp = bias + (size_t)s * BIAS_N + u.pn * BM + wc * 32 + 8 * fq;
;         const f32x4 ba0 = *(const f32x4*)bp, ba1 = *(const f32x4*)(bp + 4), bb0 = *(const f32x4*)(bp + HALF), bb1 = *(const f32x4*)(bp + HALF + 4);
;         const int lane = fq * 16 + fr;
;         const float rsl0 = row_rstd(ss, u.pm * BM + wr * 64 + lane), rsl1 = row_rstd(ss, u.pm * BM + HALF + wr * 64 + lane);
; #pragma unroll
;         for (int ai = 0; ai < 2; ++ai)
; #pragma unroll
;             for (int m = 0; m < 4; ++m) { const int row = row0 + ai * HALF + m * 16; const float rs = __shfl(ai ? rsl1 : rsl0, m * 16 + fr); bf16_t* rowp = O + (size_t)row * DFF + col0;
;                 const f32x4 a0 = acc[ai][0][m][0] * rs + ba0, a1 = acc[ai][0][m][1] * rs + ba1, b0 = acc[ai][1][m][0] * rs + bb0, b1 = acc[ai][1][m][1] * rs + bb1;
;                 u32x4 w; w.x = cvt_pk_bf16(silu_mul(a0[0], b0[0]), silu_mul(a0[1], b0[1])); w.y = cvt_pk_bf16(silu_mul(a0[2], b0[2]), silu_mul(a0[3], b0[3]));
;                 w.z = cvt_pk_bf16(silu_mul(a1[0], b1[0]), silu_mul(a1[1], b1[1])); w.w = cvt_pk_bf16(silu_mul(a1[2], b1[2]), silu_mul(a1[3], b1[3]));
;                 *(u32x4*)rowp = w; }
.LBB0_1827:
	s_lshl_b32 s2, s2, 8
	s_add_i32 s13, s2, s35
	s_lshl_b64 s[2:3], s[16:17], 2
	s_add_u32 s15, s36, s2
	s_addc_u32 s16, s37, s3
	s_lshl_b32 s2, s0, 8
	s_ashr_i32 s3, s2, 31
	s_lshl_b64 s[2:3], s[2:3], 2
	v_lshl_or_b32 v164, s0, 7, v172
	s_add_u32 s0, s15, s2
	s_addc_u32 s3, s16, s3
	v_or_b32_e32 v162, s13, v170
	s_add_u32 s2, s0, s47
	v_ashrrev_i32_e32 v163, 31, v162
	s_addc_u32 s3, s3, 0
	v_lshl_add_u64 v[162:163], v[162:163], 2, s[6:7]
	v_mov_b32_e32 v74, v234
	v_mov_b32_e32 v75, v235
	v_mov_b32_e32 v76, v236
	v_mov_b32_e32 v77, v237
	v_mov_b32_e32 v78, v238
	v_mov_b32_e32 v79, v239
	v_mov_b32_e32 v80, v240
	v_mov_b32_e32 v81, v241
	v_mov_b32_e32 v66, v242
	v_mov_b32_e32 v67, v243
	v_mov_b32_e32 v68, v244
	v_mov_b32_e32 v69, v245
	v_mov_b32_e32 v70, v246
	v_mov_b32_e32 v71, v247
	v_mov_b32_e32 v72, v248
	v_mov_b32_e32 v73, v249
	v_or_b32_e32 v180, s13, v1
	v_mov_b32_e32 v162, v250
	s_waitcnt vmcnt(0)
	v_fmamk_f32 v162, v162, 0x3a000000, v177
	v_cmp_gt_f32_e32 vcc, s48, v162
	v_mul_f32_e32 v163, 0x4f800000, v162
	s_nop 0
	v_cndmask_b32_e32 v162, v162, v163, vcc
	v_sqrt_f32_e32 v163, v162
	s_nop 0
	v_add_u32_e32 v165, -1, v163
	v_fma_f32 v166, -v165, v163, v162
	v_cmp_ge_f32_e64 s[2:3], 0, v166
	v_add_u32_e32 v166, 1, v163
	s_nop 0
	v_cndmask_b32_e64 v165, v163, v165, s[2:3]
	v_fma_f32 v163, -v166, v163, v162
	v_cmp_lt_f32_e64 s[2:3], 0, v163
	s_nop 1
	v_cndmask_b32_e64 v163, v165, v166, s[2:3]
	v_mul_f32_e32 v165, 0x37800000, v163
	v_cndmask_b32_e32 v163, v163, v165, vcc
	v_cmp_class_f32_e32 vcc, v162, v178
	s_nop 1
	v_cndmask_b32_e32 v166, v163, v162, vcc
	v_add_u32_e32 v162, s13, v171
	v_ashrrev_i32_e32 v163, 31, v162
	v_lshl_add_u64 v[162:163], v[162:163], 2, s[6:7]
	v_mov_b32_e32 v162, v251
	v_fmamk_f32 v162, v162, 0x3a000000, v177
	v_cmp_gt_f32_e32 vcc, s48, v162
	v_mul_f32_e32 v163, 0x4f800000, v162
	s_nop 0
	v_cndmask_b32_e32 v162, v162, v163, vcc
	v_sqrt_f32_e32 v163, v162
	s_nop 0
	v_add_u32_e32 v165, -1, v163
	v_fma_f32 v167, -v165, v163, v162
	v_cmp_ge_f32_e64 s[2:3], 0, v167
	v_add_u32_e32 v167, 1, v163
	s_nop 0
	v_cndmask_b32_e64 v165, v163, v165, s[2:3]
	v_fma_f32 v163, -v167, v163, v162
	v_cmp_lt_f32_e64 s[2:3], 0, v163
	s_nop 1
	v_cndmask_b32_e64 v163, v165, v167, s[2:3]
	v_mul_f32_e32 v165, 0x37800000, v163
	v_cndmask_b32_e32 v163, v163, v165, vcc
	v_cmp_class_f32_e32 vcc, v162, v178
	v_ashrrev_i32_e32 v165, 31, v164
	v_lshlrev_b64 v[164:165], 1, v[164:165]
	v_cndmask_b32_e32 v181, v163, v162, vcc
	v_div_scale_f32 v162, s[2:3], v166, v166, 1.0
	v_rcp_f32_e32 v163, v162
	s_nop 0
	v_fma_f32 v167, -v162, v163, 1.0
	v_fmac_f32_e32 v163, v167, v163
	v_div_scale_f32 v167, vcc, 1.0, v166, 1.0
	v_mul_f32_e32 v168, v167, v163
	v_fma_f32 v182, -v162, v168, v167
	v_fmac_f32_e32 v168, v182, v163
	v_fma_f32 v162, -v162, v168, v167
	v_div_fmas_f32 v162, v162, v163, v168
	v_div_fixup_f32 v182, v162, v166, 1.0
	s_mov_b32 s100, 0xbfb8aa3b
	ds_bpermute_b32 v242, v179, v182
	ds_bpermute_b32 v244, v179, v182 offset:64
	ds_bpermute_b32 v246, v179, v182 offset:128
	ds_bpermute_b32 v248, v179, v182 offset:192
	v_mov_b64_e32 v[162:163], s[96:97]
	v_mad_i64_i32 v[166:167], s[2:3], v180, s46, v[162:163]
	v_lshl_add_u64 v[166:167], v[166:167], 0, v[164:165]
	s_waitcnt lgkmcnt(0)
	v_pk_fma_f32 v[142:143], v[142:143], v[242:243], v[78:79] op_sel_hi:[1,0,1]
	v_pk_fma_f32 v[144:145], v[144:145], v[242:243], v[80:81] op_sel_hi:[1,0,1]
	v_pk_fma_f32 v[134:135], v[134:135], v[242:243], v[70:71] op_sel_hi:[1,0,1]
	v_pk_fma_f32 v[136:137], v[136:137], v[242:243], v[72:73] op_sel_hi:[1,0,1]
	v_pk_fma_f32 v[138:139], v[138:139], v[242:243], v[74:75] op_sel_hi:[1,0,1]
	v_pk_fma_f32 v[140:141], v[140:141], v[242:243], v[76:77] op_sel_hi:[1,0,1]
	v_pk_fma_f32 v[130:131], v[130:131], v[242:243], v[66:67] op_sel_hi:[1,0,1]
	v_pk_fma_f32 v[132:133], v[132:133], v[242:243], v[68:69] op_sel_hi:[1,0,1]
	v_pk_mul_f32 v[234:235], v[142:143], s[100:101] op_sel_hi:[1,0]
	v_pk_mul_f32 v[236:237], v[144:145], s[100:101] op_sel_hi:[1,0]
	v_exp_f32_e32 v234, v234
	v_exp_f32_e32 v235, v235
	v_exp_f32_e32 v236, v236
	v_exp_f32_e32 v237, v237
	v_pk_add_f32 v[234:235], v[234:235], 1.0 op_sel_hi:[1,0]
	v_pk_add_f32 v[236:237], v[236:237], 1.0 op_sel_hi:[1,0]
	v_rcp_f32_e32 v234, v234
	v_rcp_f32_e32 v235, v235
	v_rcp_f32_e32 v236, v236
	v_rcp_f32_e32 v237, v237
	v_pk_mul_f32 v[134:135], v[142:143], v[134:135]
	v_pk_mul_f32 v[136:137], v[144:145], v[136:137]
	v_pk_mul_f32 v[134:135], v[134:135], v[234:235]
	v_pk_mul_f32 v[136:137], v[136:137], v[236:237]
	v_cvt_pk_bf16_f32 v238, v134, v135
	v_cvt_pk_bf16_f32 v239, v136, v137
	v_pk_mul_f32 v[234:235], v[138:139], s[100:101] op_sel_hi:[1,0]
	v_pk_mul_f32 v[236:237], v[140:141], s[100:101] op_sel_hi:[1,0]
	v_exp_f32_e32 v234, v234
	v_exp_f32_e32 v235, v235
	v_exp_f32_e32 v236, v236
	v_exp_f32_e32 v237, v237
	v_pk_add_f32 v[234:235], v[234:235], 1.0 op_sel_hi:[1,0]
	v_pk_add_f32 v[236:237], v[236:237], 1.0 op_sel_hi:[1,0]
	v_rcp_f32_e32 v234, v234
	v_rcp_f32_e32 v235, v235
	v_rcp_f32_e32 v236, v236
	v_rcp_f32_e32 v237, v237
	v_pk_mul_f32 v[130:131], v[138:139], v[130:131]
	v_pk_mul_f32 v[132:133], v[140:141], v[132:133]
	v_pk_mul_f32 v[130:131], v[130:131], v[234:235]
	v_pk_mul_f32 v[132:133], v[132:133], v[236:237]
	v_cvt_pk_bf16_f32 v240, v130, v131
	v_cvt_pk_bf16_f32 v241, v132, v133
	global_store_dwordx4 v[166:167], v[238:241], off
	v_or_b32_e32 v131, 16, v180
	v_mad_i64_i32 v[132:133], s[2:3], v131, s46, v[162:163]
	v_lshl_add_u64 v[132:133], v[132:133], 0, v[164:165]
	v_pk_fma_f32 v[126:127], v[126:127], v[244:245], v[78:79] op_sel_hi:[1,0,1]
	v_pk_fma_f32 v[128:129], v[128:129], v[244:245], v[80:81] op_sel_hi:[1,0,1]
; __device__ __forceinline__ unsigned cvt_pk_bf16(float lo, float hi) { unsigned r; asm volatile("v_cvt_pk_bf16_f32 %0, %1, %2" : "=v"(r) : "v"(lo), "v"(hi)); return r; }
; __device__ __forceinline__ float row_rstd(const float* ss, int row) { return 1.0f / sqrtf(ss[row] * (1.0f / DM) + 1e-6f); }
; __device__ __forceinline__ float silu_mul(float a, float b) { return a * b * __builtin_amdgcn_rcpf(1.0f + __builtin_amdgcn_exp2f(-a * LOG2E)); }
;     __device__ __forceinline__ void operator()(const f32x4 (&acc)[2][2][4][2], const Unit& u, int wr, int wc, int fr, int fq) const {
;         const int row0 = u.pm * BM + wr * 64 + fr, col0 = u.pn * HALF + wc * 32 + 8 * fq;
;         const int s = (u.pm < ML / BM) ? (u.pm >> 5) : 4;
;         const float* bp = bias + (size_t)s * BIAS_N + u.pn * BM + wc * 32 + 8 * fq;
;         const f32x4 ba0 = *(const f32x4*)bp, ba1 = *(const f32x4*)(bp + 4), bb0 = *(const f32x4*)(bp + HALF), bb1 = *(const f32x4*)(bp + HALF + 4);
;         const int lane = fq * 16 + fr;
;         const float rsl0 = row_rstd(ss, u.pm * BM + wr * 64 + lane), rsl1 = row_rstd(ss, u.pm * BM + HALF + wr * 64 + lane);
; #pragma unroll
;         for (int ai = 0; ai < 2; ++ai)
; #pragma unroll
;             for (int m = 0; m < 4; ++m) { const int row = row0 + ai * HALF + m * 16; const float rs = __shfl(ai ? rsl1 : rsl0, m * 16 + fr); bf16_t* rowp = O + (size_t)row * DFF + col0;
;                 const f32x4 a0 = acc[ai][0][m][0] * rs + ba0, a1 = acc[ai][0][m][1] * rs + ba1, b0 = acc[ai][1][m][0] * rs + bb0, b1 = acc[ai][1][m][1] * rs + bb1;
;                 u32x4 w; w.x = cvt_pk_bf16(silu_mul(a0[0], b0[0]), silu_mul(a0[1], b0[1])); w.y = cvt_pk_bf16(silu_mul(a0[2], b0[2]), silu_mul(a0[3], b0[3]));
;                 w.z = cvt_pk_bf16(silu_mul(a1[0], b1[0]), silu_mul(a1[1], b1[1])); w.w = cvt_pk_bf16(silu_mul(a1[2], b1[2]), silu_mul(a1[3], b1[3]));
;                 *(u32x4*)rowp = w; }
	v_pk_fma_f32 v[118:119], v[118:119], v[244:245], v[70:71] op_sel_hi:[1,0,1]
	v_pk_fma_f32 v[120:121], v[120:121], v[244:245], v[72:73] op_sel_hi:[1,0,1]
	v_pk_fma_f32 v[122:123], v[122:123], v[244:245], v[74:75] op_sel_hi:[1,0,1]
	v_pk_fma_f32 v[124:125], v[124:125], v[244:245], v[76:77] op_sel_hi:[1,0,1]
	v_pk_fma_f32 v[114:115], v[114:115], v[244:245], v[66:67] op_sel_hi:[1,0,1]
	v_pk_fma_f32 v[116:117], v[116:117], v[244:245], v[68:69] op_sel_hi:[1,0,1]
	v_pk_mul_f32 v[234:235], v[126:127], s[100:101] op_sel_hi:[1,0]
	v_pk_mul_f32 v[236:237], v[128:129], s[100:101] op_sel_hi:[1,0]
	v_exp_f32_e32 v234, v234
	v_exp_f32_e32 v235, v235
	v_exp_f32_e32 v236, v236
	v_exp_f32_e32 v237, v237
	v_pk_add_f32 v[234:235], v[234:235], 1.0 op_sel_hi:[1,0]
	v_pk_add_f32 v[236:237], v[236:237], 1.0 op_sel_hi:[1,0]
	v_rcp_f32_e32 v234, v234
	v_rcp_f32_e32 v235, v235
	v_rcp_f32_e32 v236, v236
	v_rcp_f32_e32 v237, v237
	v_pk_mul_f32 v[118:119], v[126:127], v[118:119]
	v_pk_mul_f32 v[120:121], v[128:129], v[120:121]
	v_pk_mul_f32 v[118:119], v[118:119], v[234:235]
	v_pk_mul_f32 v[120:121], v[120:121], v[236:237]
	v_cvt_pk_bf16_f32 v238, v118, v119
	v_cvt_pk_bf16_f32 v239, v120, v121
	v_pk_mul_f32 v[234:235], v[122:123], s[100:101] op_sel_hi:[1,0]
	v_pk_mul_f32 v[236:237], v[124:125], s[100:101] op_sel_hi:[1,0]
	v_exp_f32_e32 v234, v234
	v_exp_f32_e32 v235, v235
	v_exp_f32_e32 v236, v236
	v_exp_f32_e32 v237, v237
	v_pk_add_f32 v[234:235], v[234:235], 1.0 op_sel_hi:[1,0]
	v_pk_add_f32 v[236:237], v[236:237], 1.0 op_sel_hi:[1,0]
	v_rcp_f32_e32 v234, v234
	v_rcp_f32_e32 v235, v235
	v_rcp_f32_e32 v236, v236
	v_rcp_f32_e32 v237, v237
	v_pk_mul_f32 v[114:115], v[122:123], v[114:115]
	v_pk_mul_f32 v[116:117], v[124:125], v[116:117]
	v_pk_mul_f32 v[114:115], v[114:115], v[234:235]
	v_pk_mul_f32 v[116:117], v[116:117], v[236:237]
	v_cvt_pk_bf16_f32 v240, v114, v115
	v_cvt_pk_bf16_f32 v241, v116, v117
	global_store_dwordx4 v[132:133], v[238:241], off
	v_or_b32_e32 v115, 32, v180
	v_mad_i64_i32 v[116:117], s[2:3], v115, s46, v[162:163]
	v_lshl_add_u64 v[116:117], v[116:117], 0, v[164:165]
	v_pk_fma_f32 v[110:111], v[110:111], v[246:247], v[78:79] op_sel_hi:[1,0,1]
	v_pk_fma_f32 v[112:113], v[112:113], v[246:247], v[80:81] op_sel_hi:[1,0,1]
	v_pk_fma_f32 v[102:103], v[102:103], v[246:247], v[70:71] op_sel_hi:[1,0,1]
	v_pk_fma_f32 v[104:105], v[104:105], v[246:247], v[72:73] op_sel_hi:[1,0,1]
	v_pk_fma_f32 v[106:107], v[106:107], v[246:247], v[74:75] op_sel_hi:[1,0,1]
	v_pk_fma_f32 v[108:109], v[108:109], v[246:247], v[76:77] op_sel_hi:[1,0,1]
	v_pk_fma_f32 v[98:99], v[98:99], v[246:247], v[66:67] op_sel_hi:[1,0,1]
	v_pk_fma_f32 v[100:101], v[100:101], v[246:247], v[68:69] op_sel_hi:[1,0,1]
	v_pk_mul_f32 v[234:235], v[110:111], s[100:101] op_sel_hi:[1,0]
	v_pk_mul_f32 v[236:237], v[112:113], s[100:101] op_sel_hi:[1,0]
	v_exp_f32_e32 v234, v234
	v_exp_f32_e32 v235, v235
	v_exp_f32_e32 v236, v236
	v_exp_f32_e32 v237, v237
	v_pk_add_f32 v[234:235], v[234:235], 1.0 op_sel_hi:[1,0]
	v_pk_add_f32 v[236:237], v[236:237], 1.0 op_sel_hi:[1,0]
	v_rcp_f32_e32 v234, v234
	v_rcp_f32_e32 v235, v235
	v_rcp_f32_e32 v236, v236
	v_rcp_f32_e32 v237, v237
	v_pk_mul_f32 v[102:103], v[110:111], v[102:103]
	v_pk_mul_f32 v[104:105], v[112:113], v[104:105]
	v_pk_mul_f32 v[102:103], v[102:103], v[234:235]
	v_pk_mul_f32 v[104:105], v[104:105], v[236:237]
	v_cvt_pk_bf16_f32 v238, v102, v103
	v_cvt_pk_bf16_f32 v239, v104, v105
	v_pk_mul_f32 v[234:235], v[106:107], s[100:101] op_sel_hi:[1,0]
	v_pk_mul_f32 v[236:237], v[108:109], s[100:101] op_sel_hi:[1,0]
	v_exp_f32_e32 v234, v234
	v_exp_f32_e32 v235, v235
	v_exp_f32_e32 v236, v236
	v_exp_f32_e32 v237, v237
	v_pk_add_f32 v[234:235], v[234:235], 1.0 op_sel_hi:[1,0]
	v_pk_add_f32 v[236:237], v[236:237], 1.0 op_sel_hi:[1,0]
	v_rcp_f32_e32 v234, v234
	v_rcp_f32_e32 v235, v235
	v_rcp_f32_e32 v236, v236
	v_rcp_f32_e32 v237, v237
	v_pk_mul_f32 v[98:99], v[106:107], v[98:99]
	v_pk_mul_f32 v[100:101], v[108:109], v[100:101]
	v_pk_mul_f32 v[98:99], v[98:99], v[234:235]
	v_pk_mul_f32 v[100:101], v[100:101], v[236:237]
	v_cvt_pk_bf16_f32 v240, v98, v99
	v_cvt_pk_bf16_f32 v241, v100, v101
	global_store_dwordx4 v[116:117], v[238:241], off
	v_or_b32_e32 v99, 48, v180
	v_mad_i64_i32 v[100:101], s[2:3], v99, s46, v[162:163]
	v_lshl_add_u64 v[100:101], v[100:101], 0, v[164:165]
	v_pk_fma_f32 v[94:95], v[94:95], v[248:249], v[78:79] op_sel_hi:[1,0,1]
	v_pk_fma_f32 v[96:97], v[96:97], v[248:249], v[80:81] op_sel_hi:[1,0,1]
	v_pk_fma_f32 v[86:87], v[86:87], v[248:249], v[70:71] op_sel_hi:[1,0,1]
	v_pk_fma_f32 v[88:89], v[88:89], v[248:249], v[72:73] op_sel_hi:[1,0,1]
	v_pk_fma_f32 v[90:91], v[90:91], v[248:249], v[74:75] op_sel_hi:[1,0,1]
	v_pk_fma_f32 v[92:93], v[92:93], v[248:249], v[76:77] op_sel_hi:[1,0,1]
	v_pk_fma_f32 v[82:83], v[82:83], v[248:249], v[66:67] op_sel_hi:[1,0,1]
	v_pk_fma_f32 v[84:85], v[84:85], v[248:249], v[68:69] op_sel_hi:[1,0,1]
	v_pk_mul_f32 v[234:235], v[94:95], s[100:101] op_sel_hi:[1,0]
	v_pk_mul_f32 v[236:237], v[96:97], s[100:101] op_sel_hi:[1,0]
	v_exp_f32_e32 v234, v234
	v_exp_f32_e32 v235, v235
	v_exp_f32_e32 v236, v236
	v_exp_f32_e32 v237, v237
	v_pk_add_f32 v[234:235], v[234:235], 1.0 op_sel_hi:[1,0]
	v_pk_add_f32 v[236:237], v[236:237], 1.0 op_sel_hi:[1,0]
	v_rcp_f32_e32 v234, v234
	v_rcp_f32_e32 v235, v235
	v_rcp_f32_e32 v236, v236
	v_rcp_f32_e32 v237, v237
	v_pk_mul_f32 v[86:87], v[94:95], v[86:87]
	v_pk_mul_f32 v[88:89], v[96:97], v[88:89]
	v_pk_mul_f32 v[86:87], v[86:87], v[234:235]
	v_pk_mul_f32 v[88:89], v[88:89], v[236:237]
	v_cvt_pk_bf16_f32 v238, v86, v87
	v_cvt_pk_bf16_f32 v239, v88, v89
	v_pk_mul_f32 v[234:235], v[90:91], s[100:101] op_sel_hi:[1,0]
; __device__ __forceinline__ unsigned cvt_pk_bf16(float lo, float hi) { unsigned r; asm volatile("v_cvt_pk_bf16_f32 %0, %1, %2" : "=v"(r) : "v"(lo), "v"(hi)); return r; }
; __device__ __forceinline__ float row_rstd(const float* ss, int row) { return 1.0f / sqrtf(ss[row] * (1.0f / DM) + 1e-6f); }
; __device__ __forceinline__ float silu_mul(float a, float b) { return a * b * __builtin_amdgcn_rcpf(1.0f + __builtin_amdgcn_exp2f(-a * LOG2E)); }
;     __device__ __forceinline__ void operator()(const f32x4 (&acc)[2][2][4][2], const Unit& u, int wr, int wc, int fr, int fq) const {
;     ...
;         const float rsl0 = row_rstd(ss, u.pm * BM + wr * 64 + lane), rsl1 = row_rstd(ss, u.pm * BM + HALF + wr * 64 + lane);
; #pragma unroll
;         for (int ai = 0; ai < 2; ++ai)
; #pragma unroll
;             for (int m = 0; m < 4; ++m) { const int row = row0 + ai * HALF + m * 16; const float rs = __shfl(ai ? rsl1 : rsl0, m * 16 + fr); bf16_t* rowp = O + (size_t)row * DFF + col0;
;                 const f32x4 a0 = acc[ai][0][m][0] * rs + ba0, a1 = acc[ai][0][m][1] * rs + ba1, b0 = acc[ai][1][m][0] * rs + bb0, b1 = acc[ai][1][m][1] * rs + bb1;
;                 u32x4 w; w.x = cvt_pk_bf16(silu_mul(a0[0], b0[0]), silu_mul(a0[1], b0[1])); w.y = cvt_pk_bf16(silu_mul(a0[2], b0[2]), silu_mul(a0[3], b0[3]));
;                 w.z = cvt_pk_bf16(silu_mul(a1[0], b1[0]), silu_mul(a1[1], b1[1])); w.w = cvt_pk_bf16(silu_mul(a1[2], b1[2]), silu_mul(a1[3], b1[3]));
;                 *(u32x4*)rowp = w; }
	v_pk_mul_f32 v[236:237], v[92:93], s[100:101] op_sel_hi:[1,0]
	v_exp_f32_e32 v234, v234
	v_exp_f32_e32 v235, v235
	v_exp_f32_e32 v236, v236
	v_exp_f32_e32 v237, v237
	v_pk_add_f32 v[234:235], v[234:235], 1.0 op_sel_hi:[1,0]
	v_pk_add_f32 v[236:237], v[236:237], 1.0 op_sel_hi:[1,0]
	v_rcp_f32_e32 v234, v234
	v_rcp_f32_e32 v235, v235
	v_rcp_f32_e32 v236, v236
	v_rcp_f32_e32 v237, v237
	v_pk_mul_f32 v[82:83], v[90:91], v[82:83]
	v_pk_mul_f32 v[84:85], v[92:93], v[84:85]
	v_pk_mul_f32 v[82:83], v[82:83], v[234:235]
	v_pk_mul_f32 v[84:85], v[84:85], v[236:237]
	v_cvt_pk_bf16_f32 v240, v82, v83
	v_cvt_pk_bf16_f32 v241, v84, v85
	global_store_dwordx4 v[100:101], v[238:241], off
	s_nop 1
	v_div_scale_f32 v82, s[2:3], v181, v181, 1.0
	v_rcp_f32_e32 v84, v82
	v_add_u32_e32 v83, 0x80, v180
	v_fma_f32 v85, -v82, v84, 1.0
	v_fmac_f32_e32 v84, v85, v84
	v_div_scale_f32 v85, vcc, 1.0, v181, 1.0
	v_mul_f32_e32 v86, v85, v84
	v_fma_f32 v87, -v82, v86, v85
	v_fmac_f32_e32 v86, v87, v84
	v_fma_f32 v82, -v82, v86, v85
	v_div_fmas_f32 v82, v82, v84, v86
	v_div_fixup_f32 v82, v82, v181, 1.0
	ds_bpermute_b32 v242, v179, v82
	ds_bpermute_b32 v244, v179, v82 offset:64
	ds_bpermute_b32 v246, v179, v82 offset:128
	ds_bpermute_b32 v248, v179, v82 offset:192
	v_mad_i64_i32 v[86:87], s[2:3], v83, s46, v[162:163]
	v_lshl_add_u64 v[86:87], v[86:87], 0, v[164:165]
	s_and_b64 vcc, s[38:39], exec
	s_waitcnt lgkmcnt(0)
	v_pk_fma_f32 v[62:63], v[62:63], v[242:243], v[78:79] op_sel_hi:[1,0,1]
	v_pk_fma_f32 v[64:65], v[64:65], v[242:243], v[80:81] op_sel_hi:[1,0,1]
	v_pk_fma_f32 v[54:55], v[54:55], v[242:243], v[70:71] op_sel_hi:[1,0,1]
	v_pk_fma_f32 v[56:57], v[56:57], v[242:243], v[72:73] op_sel_hi:[1,0,1]
	v_pk_fma_f32 v[58:59], v[58:59], v[242:243], v[74:75] op_sel_hi:[1,0,1]
	v_pk_fma_f32 v[60:61], v[60:61], v[242:243], v[76:77] op_sel_hi:[1,0,1]
	v_pk_fma_f32 v[50:51], v[50:51], v[242:243], v[66:67] op_sel_hi:[1,0,1]
	v_pk_fma_f32 v[52:53], v[52:53], v[242:243], v[68:69] op_sel_hi:[1,0,1]
	v_pk_mul_f32 v[234:235], v[62:63], s[100:101] op_sel_hi:[1,0]
	v_pk_mul_f32 v[236:237], v[64:65], s[100:101] op_sel_hi:[1,0]
	v_exp_f32_e32 v234, v234
	v_exp_f32_e32 v235, v235
	v_exp_f32_e32 v236, v236
	v_exp_f32_e32 v237, v237
	v_pk_add_f32 v[234:235], v[234:235], 1.0 op_sel_hi:[1,0]
	v_pk_add_f32 v[236:237], v[236:237], 1.0 op_sel_hi:[1,0]
	v_rcp_f32_e32 v234, v234
	v_rcp_f32_e32 v235, v235
	v_rcp_f32_e32 v236, v236
	v_rcp_f32_e32 v237, v237
	v_pk_mul_f32 v[54:55], v[62:63], v[54:55]
	v_pk_mul_f32 v[56:57], v[64:65], v[56:57]
	v_pk_mul_f32 v[54:55], v[54:55], v[234:235]
	v_pk_mul_f32 v[56:57], v[56:57], v[236:237]
	v_cvt_pk_bf16_f32 v238, v54, v55
	v_cvt_pk_bf16_f32 v239, v56, v57
	v_pk_mul_f32 v[234:235], v[58:59], s[100:101] op_sel_hi:[1,0]
	v_pk_mul_f32 v[236:237], v[60:61], s[100:101] op_sel_hi:[1,0]
	v_exp_f32_e32 v234, v234
	v_exp_f32_e32 v235, v235
	v_exp_f32_e32 v236, v236
	v_exp_f32_e32 v237, v237
	v_pk_add_f32 v[234:235], v[234:235], 1.0 op_sel_hi:[1,0]
	v_pk_add_f32 v[236:237], v[236:237], 1.0 op_sel_hi:[1,0]
	v_rcp_f32_e32 v234, v234
	v_rcp_f32_e32 v235, v235
	v_rcp_f32_e32 v236, v236
	v_rcp_f32_e32 v237, v237
	v_pk_mul_f32 v[50:51], v[58:59], v[50:51]
	v_pk_mul_f32 v[52:53], v[60:61], v[52:53]
	v_pk_mul_f32 v[50:51], v[50:51], v[234:235]
	v_pk_mul_f32 v[52:53], v[52:53], v[236:237]
	v_cvt_pk_bf16_f32 v240, v50, v51
	v_cvt_pk_bf16_f32 v241, v52, v53
	global_store_dwordx4 v[86:87], v[238:241], off
	v_add_u32_e32 v51, 0x90, v180
	v_mad_i64_i32 v[52:53], s[2:3], v51, s46, v[162:163]
	v_lshl_add_u64 v[52:53], v[52:53], 0, v[164:165]
	v_pk_fma_f32 v[46:47], v[46:47], v[244:245], v[78:79] op_sel_hi:[1,0,1]
	v_pk_fma_f32 v[48:49], v[48:49], v[244:245], v[80:81] op_sel_hi:[1,0,1]
	v_pk_fma_f32 v[38:39], v[38:39], v[244:245], v[70:71] op_sel_hi:[1,0,1]
	v_pk_fma_f32 v[40:41], v[40:41], v[244:245], v[72:73] op_sel_hi:[1,0,1]
	v_pk_fma_f32 v[42:43], v[42:43], v[244:245], v[74:75] op_sel_hi:[1,0,1]
	v_pk_fma_f32 v[44:45], v[44:45], v[244:245], v[76:77] op_sel_hi:[1,0,1]
	v_pk_fma_f32 v[34:35], v[34:35], v[244:245], v[66:67] op_sel_hi:[1,0,1]
	v_pk_fma_f32 v[36:37], v[36:37], v[244:245], v[68:69] op_sel_hi:[1,0,1]
	v_pk_mul_f32 v[234:235], v[46:47], s[100:101] op_sel_hi:[1,0]
	v_pk_mul_f32 v[236:237], v[48:49], s[100:101] op_sel_hi:[1,0]
	v_exp_f32_e32 v234, v234
	v_exp_f32_e32 v235, v235
	v_exp_f32_e32 v236, v236
	v_exp_f32_e32 v237, v237
	v_pk_add_f32 v[234:235], v[234:235], 1.0 op_sel_hi:[1,0]
	v_pk_add_f32 v[236:237], v[236:237], 1.0 op_sel_hi:[1,0]
	v_rcp_f32_e32 v234, v234
	v_rcp_f32_e32 v235, v235
	v_rcp_f32_e32 v236, v236
	v_rcp_f32_e32 v237, v237
	v_pk_mul_f32 v[38:39], v[46:47], v[38:39]
	v_pk_mul_f32 v[40:41], v[48:49], v[40:41]
	v_pk_mul_f32 v[38:39], v[38:39], v[234:235]
	v_pk_mul_f32 v[40:41], v[40:41], v[236:237]
	v_cvt_pk_bf16_f32 v238, v38, v39
	v_cvt_pk_bf16_f32 v239, v40, v41
	v_pk_mul_f32 v[234:235], v[42:43], s[100:101] op_sel_hi:[1,0]
	v_pk_mul_f32 v[236:237], v[44:45], s[100:101] op_sel_hi:[1,0]
	v_exp_f32_e32 v234, v234
; __device__ __forceinline__ unsigned cvt_pk_bf16(float lo, float hi) { unsigned r; asm volatile("v_cvt_pk_bf16_f32 %0, %1, %2" : "=v"(r) : "v"(lo), "v"(hi)); return r; }
; __device__ __forceinline__ float silu_mul(float a, float b) { return a * b * __builtin_amdgcn_rcpf(1.0f + __builtin_amdgcn_exp2f(-a * LOG2E)); }
; #define PG8_BAR __builtin_amdgcn_s_barrier()
;     __device__ __forceinline__ void operator()(const f32x4 (&acc)[2][2][4][2], const Unit& u, int wr, int wc, int fr, int fq) const {
;     ...
;             for (int m = 0; m < 4; ++m) { const int row = row0 + ai * HALF + m * 16; const float rs = __shfl(ai ? rsl1 : rsl0, m * 16 + fr); bf16_t* rowp = O + (size_t)row * DFF + col0;
;                 const f32x4 a0 = acc[ai][0][m][0] * rs + ba0, a1 = acc[ai][0][m][1] * rs + ba1, b0 = acc[ai][1][m][0] * rs + bb0, b1 = acc[ai][1][m][1] * rs + bb1;
;                 u32x4 w; w.x = cvt_pk_bf16(silu_mul(a0[0], b0[0]), silu_mul(a0[1], b0[1])); w.y = cvt_pk_bf16(silu_mul(a0[2], b0[2]), silu_mul(a0[3], b0[3]));
;                 w.z = cvt_pk_bf16(silu_mul(a1[0], b1[0]), silu_mul(a1[1], b1[1])); w.w = cvt_pk_bf16(silu_mul(a1[2], b1[2]), silu_mul(a1[3], b1[3]));
;                 *(u32x4*)rowp = w; }
; template <class Epi, class Sched, bool ALIGN_EPI = false, bool SP2 = false>
; __device__ __forceinline__ void gemm_phase(LAS unsigned char* lds, const Gemm g, const Sched& S, const Epi& E) {
;     ...
;         if (!has_next) break;
; #pragma unroll
;         for (int a = 0; a < 2; ++a)
; #pragma unroll
;             for (int b = 0; b < 2; ++b)
; #pragma unroll
;                 for (int m = 0; m < 4; ++m)
; #pragma unroll
;                     for (int n = 0; n < 2; ++n) acc[a][b][m][n] = (f32x4){0.f, 0.f, 0.f, 0.f};
;         cur = nxt; cA = nA; cB = nB; ++ui;
;         if constexpr (ALIGN_EPI) { if (wr == 1) PG8_BAR; }
	v_exp_f32_e32 v235, v235
	v_exp_f32_e32 v236, v236
	v_exp_f32_e32 v237, v237
	v_pk_add_f32 v[234:235], v[234:235], 1.0 op_sel_hi:[1,0]
	v_pk_add_f32 v[236:237], v[236:237], 1.0 op_sel_hi:[1,0]
	v_rcp_f32_e32 v234, v234
	v_rcp_f32_e32 v235, v235
	v_rcp_f32_e32 v236, v236
	v_rcp_f32_e32 v237, v237
	v_pk_mul_f32 v[34:35], v[42:43], v[34:35]
	v_pk_mul_f32 v[36:37], v[44:45], v[36:37]
	v_pk_mul_f32 v[34:35], v[34:35], v[234:235]
	v_pk_mul_f32 v[36:37], v[36:37], v[236:237]
	v_cvt_pk_bf16_f32 v240, v34, v35
	v_cvt_pk_bf16_f32 v241, v36, v37
	global_store_dwordx4 v[52:53], v[238:241], off
	v_add_u32_e32 v35, 0xa0, v180
	v_mad_i64_i32 v[36:37], s[2:3], v35, s46, v[162:163]
	v_lshl_add_u64 v[36:37], v[36:37], 0, v[164:165]
	v_pk_fma_f32 v[30:31], v[30:31], v[246:247], v[78:79] op_sel_hi:[1,0,1]
	v_pk_fma_f32 v[32:33], v[32:33], v[246:247], v[80:81] op_sel_hi:[1,0,1]
	v_pk_fma_f32 v[22:23], v[22:23], v[246:247], v[70:71] op_sel_hi:[1,0,1]
	v_pk_fma_f32 v[24:25], v[24:25], v[246:247], v[72:73] op_sel_hi:[1,0,1]
	v_pk_fma_f32 v[26:27], v[26:27], v[246:247], v[74:75] op_sel_hi:[1,0,1]
	v_pk_fma_f32 v[28:29], v[28:29], v[246:247], v[76:77] op_sel_hi:[1,0,1]
	v_pk_fma_f32 v[18:19], v[18:19], v[246:247], v[66:67] op_sel_hi:[1,0,1]
	v_pk_fma_f32 v[20:21], v[20:21], v[246:247], v[68:69] op_sel_hi:[1,0,1]
	v_pk_mul_f32 v[234:235], v[30:31], s[100:101] op_sel_hi:[1,0]
	v_pk_mul_f32 v[236:237], v[32:33], s[100:101] op_sel_hi:[1,0]
	v_exp_f32_e32 v234, v234
	v_exp_f32_e32 v235, v235
	v_exp_f32_e32 v236, v236
	v_exp_f32_e32 v237, v237
	v_pk_add_f32 v[234:235], v[234:235], 1.0 op_sel_hi:[1,0]
	v_pk_add_f32 v[236:237], v[236:237], 1.0 op_sel_hi:[1,0]
	v_rcp_f32_e32 v234, v234
	v_rcp_f32_e32 v235, v235
	v_rcp_f32_e32 v236, v236
	v_rcp_f32_e32 v237, v237
	v_pk_mul_f32 v[22:23], v[30:31], v[22:23]
	v_pk_mul_f32 v[24:25], v[32:33], v[24:25]
	v_pk_mul_f32 v[22:23], v[22:23], v[234:235]
	v_pk_mul_f32 v[24:25], v[24:25], v[236:237]
	v_cvt_pk_bf16_f32 v238, v22, v23
	v_cvt_pk_bf16_f32 v239, v24, v25
	v_pk_mul_f32 v[234:235], v[26:27], s[100:101] op_sel_hi:[1,0]
	v_pk_mul_f32 v[236:237], v[28:29], s[100:101] op_sel_hi:[1,0]
	v_exp_f32_e32 v234, v234
	v_exp_f32_e32 v235, v235
	v_exp_f32_e32 v236, v236
	v_exp_f32_e32 v237, v237
	v_pk_add_f32 v[234:235], v[234:235], 1.0 op_sel_hi:[1,0]
	v_pk_add_f32 v[236:237], v[236:237], 1.0 op_sel_hi:[1,0]
	v_rcp_f32_e32 v234, v234
	v_rcp_f32_e32 v235, v235
	v_rcp_f32_e32 v236, v236
	v_rcp_f32_e32 v237, v237
	v_pk_mul_f32 v[18:19], v[26:27], v[18:19]
	v_pk_mul_f32 v[20:21], v[28:29], v[20:21]
	v_pk_mul_f32 v[18:19], v[18:19], v[234:235]
	v_pk_mul_f32 v[20:21], v[20:21], v[236:237]
	v_cvt_pk_bf16_f32 v240, v18, v19
	v_cvt_pk_bf16_f32 v241, v20, v21
	global_store_dwordx4 v[36:37], v[238:241], off
	v_add_u32_e32 v19, 0xb0, v180
	v_mad_i64_i32 v[20:21], s[2:3], v19, s46, v[162:163]
	v_lshl_add_u64 v[20:21], v[20:21], 0, v[164:165]
	s_mov_b64 s[2:3], -1
	v_pk_fma_f32 v[14:15], v[14:15], v[248:249], v[78:79] op_sel_hi:[1,0,1]
	v_pk_fma_f32 v[16:17], v[16:17], v[248:249], v[80:81] op_sel_hi:[1,0,1]
	v_pk_fma_f32 v[6:7], v[6:7], v[248:249], v[70:71] op_sel_hi:[1,0,1]
	v_pk_fma_f32 v[8:9], v[8:9], v[248:249], v[72:73] op_sel_hi:[1,0,1]
	v_pk_fma_f32 v[10:11], v[10:11], v[248:249], v[74:75] op_sel_hi:[1,0,1]
	v_pk_fma_f32 v[12:13], v[12:13], v[248:249], v[76:77] op_sel_hi:[1,0,1]
	v_pk_fma_f32 v[2:3], v[2:3], v[248:249], v[66:67] op_sel_hi:[1,0,1]
	v_pk_fma_f32 v[4:5], v[4:5], v[248:249], v[68:69] op_sel_hi:[1,0,1]
	v_pk_mul_f32 v[234:235], v[14:15], s[100:101] op_sel_hi:[1,0]
	v_pk_mul_f32 v[236:237], v[16:17], s[100:101] op_sel_hi:[1,0]
	v_exp_f32_e32 v234, v234
	v_exp_f32_e32 v235, v235
	v_exp_f32_e32 v236, v236
	v_exp_f32_e32 v237, v237
	v_pk_add_f32 v[234:235], v[234:235], 1.0 op_sel_hi:[1,0]
	v_pk_add_f32 v[236:237], v[236:237], 1.0 op_sel_hi:[1,0]
	v_rcp_f32_e32 v234, v234
	v_rcp_f32_e32 v235, v235
	v_rcp_f32_e32 v236, v236
	v_rcp_f32_e32 v237, v237
	v_pk_mul_f32 v[6:7], v[14:15], v[6:7]
	v_pk_mul_f32 v[8:9], v[16:17], v[8:9]
	v_pk_mul_f32 v[6:7], v[6:7], v[234:235]
	v_pk_mul_f32 v[8:9], v[8:9], v[236:237]
	v_cvt_pk_bf16_f32 v238, v6, v7
	v_cvt_pk_bf16_f32 v239, v8, v9
	v_pk_mul_f32 v[234:235], v[10:11], s[100:101] op_sel_hi:[1,0]
	v_pk_mul_f32 v[236:237], v[12:13], s[100:101] op_sel_hi:[1,0]
	v_exp_f32_e32 v234, v234
	v_exp_f32_e32 v235, v235
	v_exp_f32_e32 v236, v236
	v_exp_f32_e32 v237, v237
	v_pk_add_f32 v[234:235], v[234:235], 1.0 op_sel_hi:[1,0]
	v_pk_add_f32 v[236:237], v[236:237], 1.0 op_sel_hi:[1,0]
	v_rcp_f32_e32 v234, v234
	v_rcp_f32_e32 v235, v235
	v_rcp_f32_e32 v236, v236
	v_rcp_f32_e32 v237, v237
	v_pk_mul_f32 v[2:3], v[10:11], v[2:3]
	v_pk_mul_f32 v[4:5], v[12:13], v[4:5]
	v_pk_mul_f32 v[2:3], v[2:3], v[234:235]
	v_pk_mul_f32 v[4:5], v[4:5], v[236:237]
	v_cvt_pk_bf16_f32 v240, v2, v3
	v_cvt_pk_bf16_f32 v241, v4, v5
	global_store_dwordx4 v[20:21], v[238:241], off
	s_cbranch_vccz .LBB0_1818
	s_andn2_b64 vcc, exec, s[4:5]
	s_cbranch_vccnz .LBB0_1817
	s_barrier
	s_branch .LBB0_1817

; __device__ __forceinline__ unsigned cvt_pk_bf16(float lo, float hi) { unsigned r; asm volatile("v_cvt_pk_bf16_f32 %0, %1, %2" : "=v"(r) : "v"(lo), "v"(hi)); return r; }
; __device__ __forceinline__ float silu_mul(float a, float b) { return a * b * __builtin_amdgcn_rcpf(1.0f + __builtin_amdgcn_exp2f(-a * LOG2E)); }
; __device__ __forceinline__ float row_rstd(const float* ss, int row) { return 1.0f / sqrtf(ss[row] * (1.0f / DM) + 1e-6f); }
;     __device__ __forceinline__ void operator()(const f32x4 (&acc)[2][2][4][2], const Unit& u, int wr, int wc, int fr, int fq) const {
;         const int row0 = u.pm * BM + wr * 64 + fr, col0 = u.pn * HALF + wc * 32 + 8 * fq;
;         const int s = (u.pm < ML / BM) ? (u.pm >> 5) : 4;
;         const float* bp = bias + (size_t)s * BIAS_N + u.pn * BM + wc * 32 + 8 * fq;
;         const f32x4 ba0 = *(const f32x4*)bp, ba1 = *(const f32x4*)(bp + 4), bb0 = *(const f32x4*)(bp + HALF), bb1 = *(const f32x4*)(bp + HALF + 4);
;         const int lane = fq * 16 + fr;
;         const float rsl0 = row_rstd(ss, u.pm * BM + wr * 64 + lane), rsl1 = row_rstd(ss, u.pm * BM + HALF + wr * 64 + lane);
; #pragma unroll
;         for (int ai = 0; ai < 2; ++ai)
; #pragma unroll
;             for (int m = 0; m < 4; ++m) { const int row = row0 + ai * HALF + m * 16; const float rs = __shfl(ai ? rsl1 : rsl0, m * 16 + fr); bf16_t* rowp = O + (size_t)row * DFF + col0;
;                 const f32x4 a0 = acc[ai][0][m][0] * rs + ba0, a1 = acc[ai][0][m][1] * rs + ba1, b0 = acc[ai][1][m][0] * rs + bb0, b1 = acc[ai][1][m][1] * rs + bb1;
;                 u32x4 w; w.x = cvt_pk_bf16(silu_mul(a0[0], b0[0]), silu_mul(a0[1], b0[1])); w.y = cvt_pk_bf16(silu_mul(a0[2], b0[2]), silu_mul(a0[3], b0[3]));
;                 w.z = cvt_pk_bf16(silu_mul(a1[0], b1[0]), silu_mul(a1[1], b1[1])); w.w = cvt_pk_bf16(silu_mul(a1[2], b1[2]), silu_mul(a1[3], b1[3]));
;                 *(u32x4*)rowp = w; }
.LBB0_2921:
	s_lshl_b32 s2, s2, 8
	s_add_i32 s11, s2, s34
	s_lshl_b64 s[18:19], s[18:19], 2
	s_add_u32 s13, s35, s18
	s_addc_u32 s18, s38, s19
	s_lshl_b32 s2, s3, 8
	v_lshl_or_b32 v164, s3, 7, v172
	s_ashr_i32 s3, s2, 31
	s_lshl_b64 s[2:3], s[2:3], 2
	s_add_u32 s2, s13, s2
	s_addc_u32 s3, s18, s3
	v_or_b32_e32 v162, s11, v170
	s_add_u32 s2, s2, s44
	v_ashrrev_i32_e32 v163, 31, v162
	s_addc_u32 s3, s3, 0
	v_lshl_add_u64 v[162:163], v[162:163], 2, s[0:1]
	v_mov_b32_e32 v74, v234
	v_mov_b32_e32 v75, v235
	v_mov_b32_e32 v76, v236
	v_mov_b32_e32 v77, v237
	v_mov_b32_e32 v78, v238
	v_mov_b32_e32 v79, v239
	v_mov_b32_e32 v80, v240
	v_mov_b32_e32 v81, v241
	v_mov_b32_e32 v66, v242
	v_mov_b32_e32 v67, v243
	v_mov_b32_e32 v68, v244
	v_mov_b32_e32 v69, v245
	v_mov_b32_e32 v70, v246
	v_mov_b32_e32 v71, v247
	v_mov_b32_e32 v72, v248
	v_mov_b32_e32 v73, v249
	v_or_b32_e32 v180, s11, v1
	v_mov_b32_e32 v162, v250
	s_waitcnt vmcnt(0)
	v_fmamk_f32 v162, v162, 0x3a000000, v177
	v_cmp_gt_f32_e32 vcc, s45, v162
	v_mul_f32_e32 v163, 0x4f800000, v162
	s_nop 0
	v_cndmask_b32_e32 v162, v162, v163, vcc
	v_sqrt_f32_e32 v163, v162
	s_nop 0
	v_add_u32_e32 v165, -1, v163
	v_fma_f32 v166, -v165, v163, v162
	v_cmp_ge_f32_e64 s[2:3], 0, v166
	v_add_u32_e32 v166, 1, v163
	s_nop 0
	v_cndmask_b32_e64 v165, v163, v165, s[2:3]
	v_fma_f32 v163, -v166, v163, v162
	v_cmp_lt_f32_e64 s[2:3], 0, v163
	s_nop 1
	v_cndmask_b32_e64 v163, v165, v166, s[2:3]
	v_mul_f32_e32 v165, 0x37800000, v163
	v_cndmask_b32_e32 v163, v163, v165, vcc
	v_cmp_class_f32_e32 vcc, v162, v178
	s_nop 1
	v_cndmask_b32_e32 v166, v163, v162, vcc
	v_add_u32_e32 v162, s11, v171
	v_ashrrev_i32_e32 v163, 31, v162
	v_lshl_add_u64 v[162:163], v[162:163], 2, s[0:1]
	v_mov_b32_e32 v162, v251
	v_fmamk_f32 v162, v162, 0x3a000000, v177
	v_cmp_gt_f32_e32 vcc, s45, v162
	v_mul_f32_e32 v163, 0x4f800000, v162
	s_nop 0
	v_cndmask_b32_e32 v162, v162, v163, vcc
	v_sqrt_f32_e32 v163, v162
	s_nop 0
	v_add_u32_e32 v165, -1, v163
	v_fma_f32 v167, -v165, v163, v162
	v_cmp_ge_f32_e64 s[2:3], 0, v167
	v_add_u32_e32 v167, 1, v163
	s_nop 0
	v_cndmask_b32_e64 v165, v163, v165, s[2:3]
	v_fma_f32 v163, -v167, v163, v162
	v_cmp_lt_f32_e64 s[2:3], 0, v163
	s_nop 1
	v_cndmask_b32_e64 v163, v165, v167, s[2:3]
	v_mul_f32_e32 v165, 0x37800000, v163
	v_cndmask_b32_e32 v163, v163, v165, vcc
	v_cmp_class_f32_e32 vcc, v162, v178
	v_ashrrev_i32_e32 v165, 31, v164
	v_lshlrev_b64 v[164:165], 1, v[164:165]
	v_cndmask_b32_e32 v181, v163, v162, vcc
	v_div_scale_f32 v162, s[2:3], v166, v166, 1.0
	v_rcp_f32_e32 v163, v162
	s_nop 0
	v_fma_f32 v167, -v162, v163, 1.0
	v_fmac_f32_e32 v163, v167, v163
	v_div_scale_f32 v167, vcc, 1.0, v166, 1.0
	v_mul_f32_e32 v168, v167, v163
	v_fma_f32 v182, -v162, v168, v167
	v_fmac_f32_e32 v168, v182, v163
	v_fma_f32 v162, -v162, v168, v167
	v_div_fmas_f32 v162, v162, v163, v168
	v_div_fixup_f32 v182, v162, v166, 1.0
	s_mov_b32 s100, 0xbfb8aa3b
	ds_bpermute_b32 v242, v179, v182
	ds_bpermute_b32 v244, v179, v182 offset:64
	ds_bpermute_b32 v246, v179, v182 offset:128
	ds_bpermute_b32 v248, v179, v182 offset:192
	v_mov_b64_e32 v[162:163], s[96:97]
	v_mad_i64_i32 v[166:167], s[2:3], v180, s43, v[162:163]
	v_lshl_add_u64 v[166:167], v[166:167], 0, v[164:165]
	s_waitcnt lgkmcnt(0)
	v_pk_fma_f32 v[142:143], v[142:143], v[242:243], v[78:79] op_sel_hi:[1,0,1]
	v_pk_fma_f32 v[144:145], v[144:145], v[242:243], v[80:81] op_sel_hi:[1,0,1]
	v_pk_fma_f32 v[134:135], v[134:135], v[242:243], v[70:71] op_sel_hi:[1,0,1]
	v_pk_fma_f32 v[136:137], v[136:137], v[242:243], v[72:73] op_sel_hi:[1,0,1]
	v_pk_fma_f32 v[138:139], v[138:139], v[242:243], v[74:75] op_sel_hi:[1,0,1]
	v_pk_fma_f32 v[140:141], v[140:141], v[242:243], v[76:77] op_sel_hi:[1,0,1]
	v_pk_fma_f32 v[130:131], v[130:131], v[242:243], v[66:67] op_sel_hi:[1,0,1]
	v_pk_fma_f32 v[132:133], v[132:133], v[242:243], v[68:69] op_sel_hi:[1,0,1]
	v_pk_mul_f32 v[234:235], v[142:143], s[100:101] op_sel_hi:[1,0]
	v_pk_mul_f32 v[236:237], v[144:145], s[100:101] op_sel_hi:[1,0]
	v_exp_f32_e32 v234, v234
	v_exp_f32_e32 v235, v235
	v_exp_f32_e32 v236, v236
	v_exp_f32_e32 v237, v237
	v_pk_add_f32 v[234:235], v[234:235], 1.0 op_sel_hi:[1,0]
	v_pk_add_f32 v[236:237], v[236:237], 1.0 op_sel_hi:[1,0]
	v_rcp_f32_e32 v234, v234
	v_rcp_f32_e32 v235, v235
	v_rcp_f32_e32 v236, v236
	v_rcp_f32_e32 v237, v237
	v_pk_mul_f32 v[134:135], v[142:143], v[134:135]
	v_pk_mul_f32 v[136:137], v[144:145], v[136:137]
	v_pk_mul_f32 v[134:135], v[134:135], v[234:235]
	v_pk_mul_f32 v[136:137], v[136:137], v[236:237]
	v_cvt_pk_bf16_f32 v238, v134, v135
	v_cvt_pk_bf16_f32 v239, v136, v137
	v_pk_mul_f32 v[234:235], v[138:139], s[100:101] op_sel_hi:[1,0]
	v_pk_mul_f32 v[236:237], v[140:141], s[100:101] op_sel_hi:[1,0]
	v_exp_f32_e32 v234, v234
	v_exp_f32_e32 v235, v235
	v_exp_f32_e32 v236, v236
	v_exp_f32_e32 v237, v237
	v_pk_add_f32 v[234:235], v[234:235], 1.0 op_sel_hi:[1,0]
	v_pk_add_f32 v[236:237], v[236:237], 1.0 op_sel_hi:[1,0]
	v_rcp_f32_e32 v234, v234
	v_rcp_f32_e32 v235, v235
	v_rcp_f32_e32 v236, v236
	v_rcp_f32_e32 v237, v237
	v_pk_mul_f32 v[130:131], v[138:139], v[130:131]
	v_pk_mul_f32 v[132:133], v[140:141], v[132:133]
	v_pk_mul_f32 v[130:131], v[130:131], v[234:235]
	v_pk_mul_f32 v[132:133], v[132:133], v[236:237]
	v_cvt_pk_bf16_f32 v240, v130, v131
	v_cvt_pk_bf16_f32 v241, v132, v133
	global_store_dwordx4 v[166:167], v[238:241], off
	v_or_b32_e32 v131, 16, v180
	v_mad_i64_i32 v[132:133], s[2:3], v131, s43, v[162:163]
	v_lshl_add_u64 v[132:133], v[132:133], 0, v[164:165]
	v_pk_fma_f32 v[126:127], v[126:127], v[244:245], v[78:79] op_sel_hi:[1,0,1]
	v_pk_fma_f32 v[128:129], v[128:129], v[244:245], v[80:81] op_sel_hi:[1,0,1]
; __device__ __forceinline__ unsigned cvt_pk_bf16(float lo, float hi) { unsigned r; asm volatile("v_cvt_pk_bf16_f32 %0, %1, %2" : "=v"(r) : "v"(lo), "v"(hi)); return r; }
; __device__ __forceinline__ float row_rstd(const float* ss, int row) { return 1.0f / sqrtf(ss[row] * (1.0f / DM) + 1e-6f); }
; __device__ __forceinline__ float silu_mul(float a, float b) { return a * b * __builtin_amdgcn_rcpf(1.0f + __builtin_amdgcn_exp2f(-a * LOG2E)); }
;     __device__ __forceinline__ void operator()(const f32x4 (&acc)[2][2][4][2], const Unit& u, int wr, int wc, int fr, int fq) const {
;         const int row0 = u.pm * BM + wr * 64 + fr, col0 = u.pn * HALF + wc * 32 + 8 * fq;
;         const int s = (u.pm < ML / BM) ? (u.pm >> 5) : 4;
;         const float* bp = bias + (size_t)s * BIAS_N + u.pn * BM + wc * 32 + 8 * fq;
;         const f32x4 ba0 = *(const f32x4*)bp, ba1 = *(const f32x4*)(bp + 4), bb0 = *(const f32x4*)(bp + HALF), bb1 = *(const f32x4*)(bp + HALF + 4);
;         const int lane = fq * 16 + fr;
;         const float rsl0 = row_rstd(ss, u.pm * BM + wr * 64 + lane), rsl1 = row_rstd(ss, u.pm * BM + HALF + wr * 64 + lane);
; #pragma unroll
;         for (int ai = 0; ai < 2; ++ai)
; #pragma unroll
;             for (int m = 0; m < 4; ++m) { const int row = row0 + ai * HALF + m * 16; const float rs = __shfl(ai ? rsl1 : rsl0, m * 16 + fr); bf16_t* rowp = O + (size_t)row * DFF + col0;
;                 const f32x4 a0 = acc[ai][0][m][0] * rs + ba0, a1 = acc[ai][0][m][1] * rs + ba1, b0 = acc[ai][1][m][0] * rs + bb0, b1 = acc[ai][1][m][1] * rs + bb1;
;                 u32x4 w; w.x = cvt_pk_bf16(silu_mul(a0[0], b0[0]), silu_mul(a0[1], b0[1])); w.y = cvt_pk_bf16(silu_mul(a0[2], b0[2]), silu_mul(a0[3], b0[3]));
;                 w.z = cvt_pk_bf16(silu_mul(a1[0], b1[0]), silu_mul(a1[1], b1[1])); w.w = cvt_pk_bf16(silu_mul(a1[2], b1[2]), silu_mul(a1[3], b1[3]));
;                 *(u32x4*)rowp = w; }
	v_pk_fma_f32 v[118:119], v[118:119], v[244:245], v[70:71] op_sel_hi:[1,0,1]
	v_pk_fma_f32 v[120:121], v[120:121], v[244:245], v[72:73] op_sel_hi:[1,0,1]
	v_pk_fma_f32 v[122:123], v[122:123], v[244:245], v[74:75] op_sel_hi:[1,0,1]
	v_pk_fma_f32 v[124:125], v[124:125], v[244:245], v[76:77] op_sel_hi:[1,0,1]
	v_pk_fma_f32 v[114:115], v[114:115], v[244:245], v[66:67] op_sel_hi:[1,0,1]
	v_pk_fma_f32 v[116:117], v[116:117], v[244:245], v[68:69] op_sel_hi:[1,0,1]
	v_pk_mul_f32 v[234:235], v[126:127], s[100:101] op_sel_hi:[1,0]
	v_pk_mul_f32 v[236:237], v[128:129], s[100:101] op_sel_hi:[1,0]
	v_exp_f32_e32 v234, v234
	v_exp_f32_e32 v235, v235
	v_exp_f32_e32 v236, v236
	v_exp_f32_e32 v237, v237
	v_pk_add_f32 v[234:235], v[234:235], 1.0 op_sel_hi:[1,0]
	v_pk_add_f32 v[236:237], v[236:237], 1.0 op_sel_hi:[1,0]
	v_rcp_f32_e32 v234, v234
	v_rcp_f32_e32 v235, v235
	v_rcp_f32_e32 v236, v236
	v_rcp_f32_e32 v237, v237
	v_pk_mul_f32 v[118:119], v[126:127], v[118:119]
	v_pk_mul_f32 v[120:121], v[128:129], v[120:121]
	v_pk_mul_f32 v[118:119], v[118:119], v[234:235]
	v_pk_mul_f32 v[120:121], v[120:121], v[236:237]
	v_cvt_pk_bf16_f32 v238, v118, v119
	v_cvt_pk_bf16_f32 v239, v120, v121
	v_pk_mul_f32 v[234:235], v[122:123], s[100:101] op_sel_hi:[1,0]
	v_pk_mul_f32 v[236:237], v[124:125], s[100:101] op_sel_hi:[1,0]
	v_exp_f32_e32 v234, v234
	v_exp_f32_e32 v235, v235
	v_exp_f32_e32 v236, v236
	v_exp_f32_e32 v237, v237
	v_pk_add_f32 v[234:235], v[234:235], 1.0 op_sel_hi:[1,0]
	v_pk_add_f32 v[236:237], v[236:237], 1.0 op_sel_hi:[1,0]
	v_rcp_f32_e32 v234, v234
	v_rcp_f32_e32 v235, v235
	v_rcp_f32_e32 v236, v236
	v_rcp_f32_e32 v237, v237
	v_pk_mul_f32 v[114:115], v[122:123], v[114:115]
	v_pk_mul_f32 v[116:117], v[124:125], v[116:117]
	v_pk_mul_f32 v[114:115], v[114:115], v[234:235]
	v_pk_mul_f32 v[116:117], v[116:117], v[236:237]
	v_cvt_pk_bf16_f32 v240, v114, v115
	v_cvt_pk_bf16_f32 v241, v116, v117
	global_store_dwordx4 v[132:133], v[238:241], off
	v_or_b32_e32 v115, 32, v180
	v_mad_i64_i32 v[116:117], s[2:3], v115, s43, v[162:163]
	v_lshl_add_u64 v[116:117], v[116:117], 0, v[164:165]
	v_pk_fma_f32 v[110:111], v[110:111], v[246:247], v[78:79] op_sel_hi:[1,0,1]
	v_pk_fma_f32 v[112:113], v[112:113], v[246:247], v[80:81] op_sel_hi:[1,0,1]
	v_pk_fma_f32 v[102:103], v[102:103], v[246:247], v[70:71] op_sel_hi:[1,0,1]
	v_pk_fma_f32 v[104:105], v[104:105], v[246:247], v[72:73] op_sel_hi:[1,0,1]
	v_pk_fma_f32 v[106:107], v[106:107], v[246:247], v[74:75] op_sel_hi:[1,0,1]
	v_pk_fma_f32 v[108:109], v[108:109], v[246:247], v[76:77] op_sel_hi:[1,0,1]
	v_pk_fma_f32 v[98:99], v[98:99], v[246:247], v[66:67] op_sel_hi:[1,0,1]
	v_pk_fma_f32 v[100:101], v[100:101], v[246:247], v[68:69] op_sel_hi:[1,0,1]
	v_pk_mul_f32 v[234:235], v[110:111], s[100:101] op_sel_hi:[1,0]
	v_pk_mul_f32 v[236:237], v[112:113], s[100:101] op_sel_hi:[1,0]
	v_exp_f32_e32 v234, v234
	v_exp_f32_e32 v235, v235
	v_exp_f32_e32 v236, v236
	v_exp_f32_e32 v237, v237
	v_pk_add_f32 v[234:235], v[234:235], 1.0 op_sel_hi:[1,0]
	v_pk_add_f32 v[236:237], v[236:237], 1.0 op_sel_hi:[1,0]
	v_rcp_f32_e32 v234, v234
	v_rcp_f32_e32 v235, v235
	v_rcp_f32_e32 v236, v236
	v_rcp_f32_e32 v237, v237
	v_pk_mul_f32 v[102:103], v[110:111], v[102:103]
	v_pk_mul_f32 v[104:105], v[112:113], v[104:105]
	v_pk_mul_f32 v[102:103], v[102:103], v[234:235]
	v_pk_mul_f32 v[104:105], v[104:105], v[236:237]
	v_cvt_pk_bf16_f32 v238, v102, v103
	v_cvt_pk_bf16_f32 v239, v104, v105
	v_pk_mul_f32 v[234:235], v[106:107], s[100:101] op_sel_hi:[1,0]
	v_pk_mul_f32 v[236:237], v[108:109], s[100:101] op_sel_hi:[1,0]
	v_exp_f32_e32 v234, v234
	v_exp_f32_e32 v235, v235
	v_exp_f32_e32 v236, v236
	v_exp_f32_e32 v237, v237
	v_pk_add_f32 v[234:235], v[234:235], 1.0 op_sel_hi:[1,0]
	v_pk_add_f32 v[236:237], v[236:237], 1.0 op_sel_hi:[1,0]
	v_rcp_f32_e32 v234, v234
	v_rcp_f32_e32 v235, v235
	v_rcp_f32_e32 v236, v236
	v_rcp_f32_e32 v237, v237
	v_pk_mul_f32 v[98:99], v[106:107], v[98:99]
	v_pk_mul_f32 v[100:101], v[108:109], v[100:101]
	v_pk_mul_f32 v[98:99], v[98:99], v[234:235]
	v_pk_mul_f32 v[100:101], v[100:101], v[236:237]
	v_cvt_pk_bf16_f32 v240, v98, v99
	v_cvt_pk_bf16_f32 v241, v100, v101
	global_store_dwordx4 v[116:117], v[238:241], off
	v_or_b32_e32 v99, 48, v180
	v_mad_i64_i32 v[100:101], s[2:3], v99, s43, v[162:163]
	v_lshl_add_u64 v[100:101], v[100:101], 0, v[164:165]
	v_pk_fma_f32 v[94:95], v[94:95], v[248:249], v[78:79] op_sel_hi:[1,0,1]
	v_pk_fma_f32 v[96:97], v[96:97], v[248:249], v[80:81] op_sel_hi:[1,0,1]
	v_pk_fma_f32 v[86:87], v[86:87], v[248:249], v[70:71] op_sel_hi:[1,0,1]
	v_pk_fma_f32 v[88:89], v[88:89], v[248:249], v[72:73] op_sel_hi:[1,0,1]
	v_pk_fma_f32 v[90:91], v[90:91], v[248:249], v[74:75] op_sel_hi:[1,0,1]
	v_pk_fma_f32 v[92:93], v[92:93], v[248:249], v[76:77] op_sel_hi:[1,0,1]
	v_pk_fma_f32 v[82:83], v[82:83], v[248:249], v[66:67] op_sel_hi:[1,0,1]
	v_pk_fma_f32 v[84:85], v[84:85], v[248:249], v[68:69] op_sel_hi:[1,0,1]
	v_pk_mul_f32 v[234:235], v[94:95], s[100:101] op_sel_hi:[1,0]
	v_pk_mul_f32 v[236:237], v[96:97], s[100:101] op_sel_hi:[1,0]
	v_exp_f32_e32 v234, v234
	v_exp_f32_e32 v235, v235
	v_exp_f32_e32 v236, v236
	v_exp_f32_e32 v237, v237
	v_pk_add_f32 v[234:235], v[234:235], 1.0 op_sel_hi:[1,0]
	v_pk_add_f32 v[236:237], v[236:237], 1.0 op_sel_hi:[1,0]
	v_rcp_f32_e32 v234, v234
	v_rcp_f32_e32 v235, v235
	v_rcp_f32_e32 v236, v236
	v_rcp_f32_e32 v237, v237
	v_pk_mul_f32 v[86:87], v[94:95], v[86:87]
	v_pk_mul_f32 v[88:89], v[96:97], v[88:89]
	v_pk_mul_f32 v[86:87], v[86:87], v[234:235]
	v_pk_mul_f32 v[88:89], v[88:89], v[236:237]
	v_cvt_pk_bf16_f32 v238, v86, v87
	v_cvt_pk_bf16_f32 v239, v88, v89
	v_pk_mul_f32 v[234:235], v[90:91], s[100:101] op_sel_hi:[1,0]
; __device__ __forceinline__ unsigned cvt_pk_bf16(float lo, float hi) { unsigned r; asm volatile("v_cvt_pk_bf16_f32 %0, %1, %2" : "=v"(r) : "v"(lo), "v"(hi)); return r; }
; __device__ __forceinline__ float row_rstd(const float* ss, int row) { return 1.0f / sqrtf(ss[row] * (1.0f / DM) + 1e-6f); }
; __device__ __forceinline__ float silu_mul(float a, float b) { return a * b * __builtin_amdgcn_rcpf(1.0f + __builtin_amdgcn_exp2f(-a * LOG2E)); }
;     __device__ __forceinline__ void operator()(const f32x4 (&acc)[2][2][4][2], const Unit& u, int wr, int wc, int fr, int fq) const {
;     ...
;         const float rsl0 = row_rstd(ss, u.pm * BM + wr * 64 + lane), rsl1 = row_rstd(ss, u.pm * BM + HALF + wr * 64 + lane);
; #pragma unroll
;         for (int ai = 0; ai < 2; ++ai)
; #pragma unroll
;             for (int m = 0; m < 4; ++m) { const int row = row0 + ai * HALF + m * 16; const float rs = __shfl(ai ? rsl1 : rsl0, m * 16 + fr); bf16_t* rowp = O + (size_t)row * DFF + col0;
;                 const f32x4 a0 = acc[ai][0][m][0] * rs + ba0, a1 = acc[ai][0][m][1] * rs + ba1, b0 = acc[ai][1][m][0] * rs + bb0, b1 = acc[ai][1][m][1] * rs + bb1;
;                 u32x4 w; w.x = cvt_pk_bf16(silu_mul(a0[0], b0[0]), silu_mul(a0[1], b0[1])); w.y = cvt_pk_bf16(silu_mul(a0[2], b0[2]), silu_mul(a0[3], b0[3]));
;                 w.z = cvt_pk_bf16(silu_mul(a1[0], b1[0]), silu_mul(a1[1], b1[1])); w.w = cvt_pk_bf16(silu_mul(a1[2], b1[2]), silu_mul(a1[3], b1[3]));
;                 *(u32x4*)rowp = w; }
	v_pk_mul_f32 v[236:237], v[92:93], s[100:101] op_sel_hi:[1,0]
	v_exp_f32_e32 v234, v234
	v_exp_f32_e32 v235, v235
	v_exp_f32_e32 v236, v236
	v_exp_f32_e32 v237, v237
	v_pk_add_f32 v[234:235], v[234:235], 1.0 op_sel_hi:[1,0]
	v_pk_add_f32 v[236:237], v[236:237], 1.0 op_sel_hi:[1,0]
	v_rcp_f32_e32 v234, v234
	v_rcp_f32_e32 v235, v235
	v_rcp_f32_e32 v236, v236
	v_rcp_f32_e32 v237, v237
	v_pk_mul_f32 v[82:83], v[90:91], v[82:83]
	v_pk_mul_f32 v[84:85], v[92:93], v[84:85]
	v_pk_mul_f32 v[82:83], v[82:83], v[234:235]
	v_pk_mul_f32 v[84:85], v[84:85], v[236:237]
	v_cvt_pk_bf16_f32 v240, v82, v83
	v_cvt_pk_bf16_f32 v241, v84, v85
	global_store_dwordx4 v[100:101], v[238:241], off
	s_nop 1
	v_div_scale_f32 v82, s[2:3], v181, v181, 1.0
	v_rcp_f32_e32 v84, v82
	v_add_u32_e32 v83, 0x80, v180
	v_fma_f32 v85, -v82, v84, 1.0
	v_fmac_f32_e32 v84, v85, v84
	v_div_scale_f32 v85, vcc, 1.0, v181, 1.0
	v_mul_f32_e32 v86, v85, v84
	v_fma_f32 v87, -v82, v86, v85
	v_fmac_f32_e32 v86, v87, v84
	v_fma_f32 v82, -v82, v86, v85
	v_div_fmas_f32 v82, v82, v84, v86
	v_div_fixup_f32 v82, v82, v181, 1.0
	ds_bpermute_b32 v242, v179, v82
	ds_bpermute_b32 v244, v179, v82 offset:64
	ds_bpermute_b32 v246, v179, v82 offset:128
	ds_bpermute_b32 v248, v179, v82 offset:192
	v_mad_i64_i32 v[86:87], s[2:3], v83, s43, v[162:163]
	v_lshl_add_u64 v[86:87], v[86:87], 0, v[164:165]
	s_and_b64 vcc, s[36:37], exec
	s_waitcnt lgkmcnt(0)
	v_pk_fma_f32 v[62:63], v[62:63], v[242:243], v[78:79] op_sel_hi:[1,0,1]
	v_pk_fma_f32 v[64:65], v[64:65], v[242:243], v[80:81] op_sel_hi:[1,0,1]
	v_pk_fma_f32 v[54:55], v[54:55], v[242:243], v[70:71] op_sel_hi:[1,0,1]
	v_pk_fma_f32 v[56:57], v[56:57], v[242:243], v[72:73] op_sel_hi:[1,0,1]
	v_pk_fma_f32 v[58:59], v[58:59], v[242:243], v[74:75] op_sel_hi:[1,0,1]
	v_pk_fma_f32 v[60:61], v[60:61], v[242:243], v[76:77] op_sel_hi:[1,0,1]
	v_pk_fma_f32 v[50:51], v[50:51], v[242:243], v[66:67] op_sel_hi:[1,0,1]
	v_pk_fma_f32 v[52:53], v[52:53], v[242:243], v[68:69] op_sel_hi:[1,0,1]
	v_pk_mul_f32 v[234:235], v[62:63], s[100:101] op_sel_hi:[1,0]
	v_pk_mul_f32 v[236:237], v[64:65], s[100:101] op_sel_hi:[1,0]
	v_exp_f32_e32 v234, v234
	v_exp_f32_e32 v235, v235
	v_exp_f32_e32 v236, v236
	v_exp_f32_e32 v237, v237
	v_pk_add_f32 v[234:235], v[234:235], 1.0 op_sel_hi:[1,0]
	v_pk_add_f32 v[236:237], v[236:237], 1.0 op_sel_hi:[1,0]
	v_rcp_f32_e32 v234, v234
	v_rcp_f32_e32 v235, v235
	v_rcp_f32_e32 v236, v236
	v_rcp_f32_e32 v237, v237
	v_pk_mul_f32 v[54:55], v[62:63], v[54:55]
	v_pk_mul_f32 v[56:57], v[64:65], v[56:57]
	v_pk_mul_f32 v[54:55], v[54:55], v[234:235]
	v_pk_mul_f32 v[56:57], v[56:57], v[236:237]
	v_cvt_pk_bf16_f32 v238, v54, v55
	v_cvt_pk_bf16_f32 v239, v56, v57
	v_pk_mul_f32 v[234:235], v[58:59], s[100:101] op_sel_hi:[1,0]
	v_pk_mul_f32 v[236:237], v[60:61], s[100:101] op_sel_hi:[1,0]
	v_exp_f32_e32 v234, v234
	v_exp_f32_e32 v235, v235
	v_exp_f32_e32 v236, v236
	v_exp_f32_e32 v237, v237
	v_pk_add_f32 v[234:235], v[234:235], 1.0 op_sel_hi:[1,0]
	v_pk_add_f32 v[236:237], v[236:237], 1.0 op_sel_hi:[1,0]
	v_rcp_f32_e32 v234, v234
	v_rcp_f32_e32 v235, v235
	v_rcp_f32_e32 v236, v236
	v_rcp_f32_e32 v237, v237
	v_pk_mul_f32 v[50:51], v[58:59], v[50:51]
	v_pk_mul_f32 v[52:53], v[60:61], v[52:53]
	v_pk_mul_f32 v[50:51], v[50:51], v[234:235]
	v_pk_mul_f32 v[52:53], v[52:53], v[236:237]
	v_cvt_pk_bf16_f32 v240, v50, v51
	v_cvt_pk_bf16_f32 v241, v52, v53
	global_store_dwordx4 v[86:87], v[238:241], off
	v_add_u32_e32 v51, 0x90, v180
	v_mad_i64_i32 v[52:53], s[2:3], v51, s43, v[162:163]
	v_lshl_add_u64 v[52:53], v[52:53], 0, v[164:165]
	v_pk_fma_f32 v[46:47], v[46:47], v[244:245], v[78:79] op_sel_hi:[1,0,1]
	v_pk_fma_f32 v[48:49], v[48:49], v[244:245], v[80:81] op_sel_hi:[1,0,1]
	v_pk_fma_f32 v[38:39], v[38:39], v[244:245], v[70:71] op_sel_hi:[1,0,1]
	v_pk_fma_f32 v[40:41], v[40:41], v[244:245], v[72:73] op_sel_hi:[1,0,1]
	v_pk_fma_f32 v[42:43], v[42:43], v[244:245], v[74:75] op_sel_hi:[1,0,1]
	v_pk_fma_f32 v[44:45], v[44:45], v[244:245], v[76:77] op_sel_hi:[1,0,1]
	v_pk_fma_f32 v[34:35], v[34:35], v[244:245], v[66:67] op_sel_hi:[1,0,1]
	v_pk_fma_f32 v[36:37], v[36:37], v[244:245], v[68:69] op_sel_hi:[1,0,1]
	v_pk_mul_f32 v[234:235], v[46:47], s[100:101] op_sel_hi:[1,0]
	v_pk_mul_f32 v[236:237], v[48:49], s[100:101] op_sel_hi:[1,0]
	v_exp_f32_e32 v234, v234
	v_exp_f32_e32 v235, v235
	v_exp_f32_e32 v236, v236
	v_exp_f32_e32 v237, v237
	v_pk_add_f32 v[234:235], v[234:235], 1.0 op_sel_hi:[1,0]
	v_pk_add_f32 v[236:237], v[236:237], 1.0 op_sel_hi:[1,0]
	v_rcp_f32_e32 v234, v234
	v_rcp_f32_e32 v235, v235
	v_rcp_f32_e32 v236, v236
	v_rcp_f32_e32 v237, v237
	v_pk_mul_f32 v[38:39], v[46:47], v[38:39]
	v_pk_mul_f32 v[40:41], v[48:49], v[40:41]
	v_pk_mul_f32 v[38:39], v[38:39], v[234:235]
	v_pk_mul_f32 v[40:41], v[40:41], v[236:237]
	v_cvt_pk_bf16_f32 v238, v38, v39
	v_cvt_pk_bf16_f32 v239, v40, v41
	v_pk_mul_f32 v[234:235], v[42:43], s[100:101] op_sel_hi:[1,0]
	v_pk_mul_f32 v[236:237], v[44:45], s[100:101] op_sel_hi:[1,0]
	v_exp_f32_e32 v234, v234
; __device__ __forceinline__ unsigned cvt_pk_bf16(float lo, float hi) { unsigned r; asm volatile("v_cvt_pk_bf16_f32 %0, %1, %2" : "=v"(r) : "v"(lo), "v"(hi)); return r; }
; __device__ __forceinline__ float silu_mul(float a, float b) { return a * b * __builtin_amdgcn_rcpf(1.0f + __builtin_amdgcn_exp2f(-a * LOG2E)); }
; #define PG8_BAR __builtin_amdgcn_s_barrier()
;     __device__ __forceinline__ void operator()(const f32x4 (&acc)[2][2][4][2], const Unit& u, int wr, int wc, int fr, int fq) const {
;     ...
;             for (int m = 0; m < 4; ++m) { const int row = row0 + ai * HALF + m * 16; const float rs = __shfl(ai ? rsl1 : rsl0, m * 16 + fr); bf16_t* rowp = O + (size_t)row * DFF + col0;
;                 const f32x4 a0 = acc[ai][0][m][0] * rs + ba0, a1 = acc[ai][0][m][1] * rs + ba1, b0 = acc[ai][1][m][0] * rs + bb0, b1 = acc[ai][1][m][1] * rs + bb1;
;                 u32x4 w; w.x = cvt_pk_bf16(silu_mul(a0[0], b0[0]), silu_mul(a0[1], b0[1])); w.y = cvt_pk_bf16(silu_mul(a0[2], b0[2]), silu_mul(a0[3], b0[3]));
;                 w.z = cvt_pk_bf16(silu_mul(a1[0], b1[0]), silu_mul(a1[1], b1[1])); w.w = cvt_pk_bf16(silu_mul(a1[2], b1[2]), silu_mul(a1[3], b1[3]));
;                 *(u32x4*)rowp = w; }
; template <class Epi, class Sched, bool ALIGN_EPI = false, bool SP2 = false>
; __device__ __forceinline__ void gemm_phase(LAS unsigned char* lds, const Gemm g, const Sched& S, const Epi& E) {
;     ...
;         if (!has_next) break;
; #pragma unroll
;         for (int a = 0; a < 2; ++a)
; #pragma unroll
;             for (int b = 0; b < 2; ++b)
; #pragma unroll
;                 for (int m = 0; m < 4; ++m)
; #pragma unroll
;                     for (int n = 0; n < 2; ++n) acc[a][b][m][n] = (f32x4){0.f, 0.f, 0.f, 0.f};
;         cur = nxt; cA = nA; cB = nB; ++ui;
;         if constexpr (ALIGN_EPI) { if (wr == 1) PG8_BAR; }
	v_exp_f32_e32 v235, v235
	v_exp_f32_e32 v236, v236
	v_exp_f32_e32 v237, v237
	v_pk_add_f32 v[234:235], v[234:235], 1.0 op_sel_hi:[1,0]
	v_pk_add_f32 v[236:237], v[236:237], 1.0 op_sel_hi:[1,0]
	v_rcp_f32_e32 v234, v234
	v_rcp_f32_e32 v235, v235
	v_rcp_f32_e32 v236, v236
	v_rcp_f32_e32 v237, v237
	v_pk_mul_f32 v[34:35], v[42:43], v[34:35]
	v_pk_mul_f32 v[36:37], v[44:45], v[36:37]
	v_pk_mul_f32 v[34:35], v[34:35], v[234:235]
	v_pk_mul_f32 v[36:37], v[36:37], v[236:237]
	v_cvt_pk_bf16_f32 v240, v34, v35
	v_cvt_pk_bf16_f32 v241, v36, v37
	global_store_dwordx4 v[52:53], v[238:241], off
	v_add_u32_e32 v35, 0xa0, v180
	v_mad_i64_i32 v[36:37], s[2:3], v35, s43, v[162:163]
	v_lshl_add_u64 v[36:37], v[36:37], 0, v[164:165]
	v_pk_fma_f32 v[30:31], v[30:31], v[246:247], v[78:79] op_sel_hi:[1,0,1]
	v_pk_fma_f32 v[32:33], v[32:33], v[246:247], v[80:81] op_sel_hi:[1,0,1]
	v_pk_fma_f32 v[22:23], v[22:23], v[246:247], v[70:71] op_sel_hi:[1,0,1]
	v_pk_fma_f32 v[24:25], v[24:25], v[246:247], v[72:73] op_sel_hi:[1,0,1]
	v_pk_fma_f32 v[26:27], v[26:27], v[246:247], v[74:75] op_sel_hi:[1,0,1]
	v_pk_fma_f32 v[28:29], v[28:29], v[246:247], v[76:77] op_sel_hi:[1,0,1]
	v_pk_fma_f32 v[18:19], v[18:19], v[246:247], v[66:67] op_sel_hi:[1,0,1]
	v_pk_fma_f32 v[20:21], v[20:21], v[246:247], v[68:69] op_sel_hi:[1,0,1]
	v_pk_mul_f32 v[234:235], v[30:31], s[100:101] op_sel_hi:[1,0]
	v_pk_mul_f32 v[236:237], v[32:33], s[100:101] op_sel_hi:[1,0]
	v_exp_f32_e32 v234, v234
	v_exp_f32_e32 v235, v235
	v_exp_f32_e32 v236, v236
	v_exp_f32_e32 v237, v237
	v_pk_add_f32 v[234:235], v[234:235], 1.0 op_sel_hi:[1,0]
	v_pk_add_f32 v[236:237], v[236:237], 1.0 op_sel_hi:[1,0]
	v_rcp_f32_e32 v234, v234
	v_rcp_f32_e32 v235, v235
	v_rcp_f32_e32 v236, v236
	v_rcp_f32_e32 v237, v237
	v_pk_mul_f32 v[22:23], v[30:31], v[22:23]
	v_pk_mul_f32 v[24:25], v[32:33], v[24:25]
	v_pk_mul_f32 v[22:23], v[22:23], v[234:235]
	v_pk_mul_f32 v[24:25], v[24:25], v[236:237]
	v_cvt_pk_bf16_f32 v238, v22, v23
	v_cvt_pk_bf16_f32 v239, v24, v25
	v_pk_mul_f32 v[234:235], v[26:27], s[100:101] op_sel_hi:[1,0]
	v_pk_mul_f32 v[236:237], v[28:29], s[100:101] op_sel_hi:[1,0]
	v_exp_f32_e32 v234, v234
	v_exp_f32_e32 v235, v235
	v_exp_f32_e32 v236, v236
	v_exp_f32_e32 v237, v237
	v_pk_add_f32 v[234:235], v[234:235], 1.0 op_sel_hi:[1,0]
	v_pk_add_f32 v[236:237], v[236:237], 1.0 op_sel_hi:[1,0]
	v_rcp_f32_e32 v234, v234
	v_rcp_f32_e32 v235, v235
	v_rcp_f32_e32 v236, v236
	v_rcp_f32_e32 v237, v237
	v_pk_mul_f32 v[18:19], v[26:27], v[18:19]
	v_pk_mul_f32 v[20:21], v[28:29], v[20:21]
	v_pk_mul_f32 v[18:19], v[18:19], v[234:235]
	v_pk_mul_f32 v[20:21], v[20:21], v[236:237]
	v_cvt_pk_bf16_f32 v240, v18, v19
	v_cvt_pk_bf16_f32 v241, v20, v21
	global_store_dwordx4 v[36:37], v[238:241], off
	v_add_u32_e32 v19, 0xb0, v180
	v_mad_i64_i32 v[20:21], s[2:3], v19, s43, v[162:163]
	v_lshl_add_u64 v[20:21], v[20:21], 0, v[164:165]
	s_mov_b64 s[2:3], -1
	v_pk_fma_f32 v[14:15], v[14:15], v[248:249], v[78:79] op_sel_hi:[1,0,1]
	v_pk_fma_f32 v[16:17], v[16:17], v[248:249], v[80:81] op_sel_hi:[1,0,1]
	v_pk_fma_f32 v[6:7], v[6:7], v[248:249], v[70:71] op_sel_hi:[1,0,1]
	v_pk_fma_f32 v[8:9], v[8:9], v[248:249], v[72:73] op_sel_hi:[1,0,1]
	v_pk_fma_f32 v[10:11], v[10:11], v[248:249], v[74:75] op_sel_hi:[1,0,1]
	v_pk_fma_f32 v[12:13], v[12:13], v[248:249], v[76:77] op_sel_hi:[1,0,1]
	v_pk_fma_f32 v[2:3], v[2:3], v[248:249], v[66:67] op_sel_hi:[1,0,1]
	v_pk_fma_f32 v[4:5], v[4:5], v[248:249], v[68:69] op_sel_hi:[1,0,1]
	v_pk_mul_f32 v[234:235], v[14:15], s[100:101] op_sel_hi:[1,0]
	v_pk_mul_f32 v[236:237], v[16:17], s[100:101] op_sel_hi:[1,0]
	v_exp_f32_e32 v234, v234
	v_exp_f32_e32 v235, v235
	v_exp_f32_e32 v236, v236
	v_exp_f32_e32 v237, v237
	v_pk_add_f32 v[234:235], v[234:235], 1.0 op_sel_hi:[1,0]
	v_pk_add_f32 v[236:237], v[236:237], 1.0 op_sel_hi:[1,0]
	v_rcp_f32_e32 v234, v234
	v_rcp_f32_e32 v235, v235
	v_rcp_f32_e32 v236, v236
	v_rcp_f32_e32 v237, v237
	v_pk_mul_f32 v[6:7], v[14:15], v[6:7]
	v_pk_mul_f32 v[8:9], v[16:17], v[8:9]
	v_pk_mul_f32 v[6:7], v[6:7], v[234:235]
	v_pk_mul_f32 v[8:9], v[8:9], v[236:237]
	v_cvt_pk_bf16_f32 v238, v6, v7
	v_cvt_pk_bf16_f32 v239, v8, v9
	v_pk_mul_f32 v[234:235], v[10:11], s[100:101] op_sel_hi:[1,0]
	v_pk_mul_f32 v[236:237], v[12:13], s[100:101] op_sel_hi:[1,0]
	v_exp_f32_e32 v234, v234
	v_exp_f32_e32 v235, v235
	v_exp_f32_e32 v236, v236
	v_exp_f32_e32 v237, v237
	v_pk_add_f32 v[234:235], v[234:235], 1.0 op_sel_hi:[1,0]
	v_pk_add_f32 v[236:237], v[236:237], 1.0 op_sel_hi:[1,0]
	v_rcp_f32_e32 v234, v234
	v_rcp_f32_e32 v235, v235
	v_rcp_f32_e32 v236, v236
	v_rcp_f32_e32 v237, v237
	v_pk_mul_f32 v[2:3], v[10:11], v[2:3]
	v_pk_mul_f32 v[4:5], v[12:13], v[4:5]
	v_pk_mul_f32 v[2:3], v[2:3], v[234:235]
	v_pk_mul_f32 v[4:5], v[4:5], v[236:237]
	v_cvt_pk_bf16_f32 v240, v2, v3
	v_cvt_pk_bf16_f32 v241, v4, v5
	global_store_dwordx4 v[20:21], v[238:241], off
	s_cbranch_vccz .LBB0_2912
	s_andn2_b64 vcc, exec, s[4:5]
	s_cbranch_vccnz .LBB0_2911
	s_barrier
	s_branch .LBB0_2911
